# de-serialized GEMM epilogues: P4 rstd hoisted (quarter loads + permlane reduce), P3/P5 residual tile loads all issued up front with counted waits
# speedup vs baseline: 1.0148x; 1.0148x over previous
; __device__ __forceinline__ unsigned cvt_pk_bf16(float lo, float hi) { unsigned r; asm volatile("v_cvt_pk_bf16_f32 %0, %1, %2" : "=v"(r) : "v"(lo), "v"(hi)); return r; }
;     __device__ __forceinline__ void operator()(const f32x4 (&acc)[2][2][4][2], const Unit& u, int wr, int wc, int fr, int fq) const {
;     ...
;                 const unsigned row = row0 + ai * HALF + m * 16;
;                 const unsigned hoff = (row * 1024u + col0) * 2u;
;                 float sq = 0.f;
; #pragma unroll
;                 for (int bj = 0; bj < 2; ++bj) {
;                     const u32x4 xw = *(const u32x4*)(xbp + hoff + bj * (HALF * 2));
;                     f32x4 v0, v1;
;                     v0[0] = __uint_as_float(xw.x << 16) + acc[ai][bj][m][0][0]; v0[1] = __uint_as_float(xw.x & 0xffff0000u) + acc[ai][bj][m][0][1];
;                     v0[2] = __uint_as_float(xw.y << 16) + acc[ai][bj][m][0][2]; v0[3] = __uint_as_float(xw.y & 0xffff0000u) + acc[ai][bj][m][0][3];
;                     v1[0] = __uint_as_float(xw.z << 16) + acc[ai][bj][m][1][0]; v1[1] = __uint_as_float(xw.z & 0xffff0000u) + acc[ai][bj][m][1][1];
;                     v1[2] = __uint_as_float(xw.w << 16) + acc[ai][bj][m][1][2]; v1[3] = __uint_as_float(xw.w & 0xffff0000u) + acc[ai][bj][m][1][3];
;                     if (xout) { *(f32x4*)(xo + 2u * hoff + bj * (HALF * 4)) = v0; *(f32x4*)(xo + 2u * hoff + bj * (HALF * 4) + 16) = v1; }
;                     u32x4 w; w.x = cvt_pk_bf16(v0[0], v0[1]); w.y = cvt_pk_bf16(v0[2], v0[3]); w.z = cvt_pk_bf16(v1[0], v1[1]); w.w = cvt_pk_bf16(v1[2], v1[3]);
;                     *(u32x4*)(xbp + hoff + bj * (HALF * 2)) = w;
;                     sq += (v0[0] * v0[0] + v0[1] * v0[1]) + (v0[2] * v0[2] + v0[3] * v0[3]) + (v1[0] * v1[0] + v1[1] * v1[1]) + (v1[2] * v1[2] + v1[3] * v1[3]);
;                 }
;                 sq += __shfl_xor(sq, 16); sq += __shfl_xor(sq, 32);
;                 if (fq == 0) *(float*)(ssp + row * 64u + ssoff) = sq;
.LBB0_1062:
	v_lshl_add_u32 v154, s55, 8, v150
	v_lshl_or_b32 v155, s54, 9, v152
	v_lshl_add_u32 v160, v154, 11, v155
	v_add_u32_e32 v240, 0x8000, v160
	v_add_u32_e32 v241, 0x10000, v160
	v_add_u32_e32 v242, 0x18000, v160
	v_add_u32_e32 v243, 0x40000, v160
	v_add_u32_e32 v244, 0x48000, v160
	v_add_u32_e32 v245, 0x50000, v160
	v_add_u32_e32 v246, 0x58000, v160
	global_load_dwordx4 v[172:175], v160, s[72:73]
	global_load_dwordx4 v[176:179], v160, s[72:73] offset:256
	global_load_dwordx4 v[180:183], v240, s[72:73]
	global_load_dwordx4 v[184:187], v240, s[72:73] offset:256
	global_load_dwordx4 v[188:191], v241, s[72:73]
	global_load_dwordx4 v[192:195], v241, s[72:73] offset:256
	global_load_dwordx4 v[196:199], v242, s[72:73]
	global_load_dwordx4 v[200:203], v242, s[72:73] offset:256
	global_load_dwordx4 v[208:211], v243, s[72:73]
	global_load_dwordx4 v[212:215], v243, s[72:73] offset:256
	global_load_dwordx4 v[216:219], v244, s[72:73]
	global_load_dwordx4 v[220:223], v244, s[72:73] offset:256
	global_load_dwordx4 v[224:227], v245, s[72:73]
	global_load_dwordx4 v[228:231], v245, s[72:73] offset:256
	global_load_dwordx4 v[232:235], v246, s[72:73]
	global_load_dwordx4 v[236:239], v246, s[72:73] offset:256
	s_lshl_b32 s24, s54, 4
	s_or_b32 s24, s24, s92
	s_add_u32 s54, s90, s24
	s_addc_u32 s55, s91, 0
	s_waitcnt vmcnt(15)
	v_mov_b32_e32 v156, v172
	v_mov_b32_e32 v157, v173
	v_mov_b32_e32 v158, v174
	v_mov_b32_e32 v159, v175
	v_lshlrev_b32_e32 v161, 16, v156
	v_and_b32_e32 v156, 0xffff0000, v156
	v_add_f32_e32 v125, v125, v156
	v_lshlrev_b32_e32 v156, 16, v157
	v_add_f32_e32 v126, v126, v156
	v_and_b32_e32 v156, 0xffff0000, v157
	v_add_f32_e32 v127, v127, v156
	v_lshlrev_b32_e32 v156, 16, v158
	v_add_f32_e32 v156, v120, v156
	v_and_b32_e32 v120, 0xffff0000, v158
	v_add_f32_e32 v157, v121, v120
	v_lshlrev_b32_e32 v120, 16, v159
	v_add_f32_e32 v158, v122, v120
	v_and_b32_e32 v120, 0xffff0000, v159
	v_add_f32_e32 v124, v124, v161
	v_add_f32_e32 v159, v123, v120
	v_cvt_pk_bf16_f32 v120, v124, v125
	v_cvt_pk_bf16_f32 v121, v126, v127
	v_cvt_pk_bf16_f32 v122, v156, v157
	v_cvt_pk_bf16_f32 v123, v158, v159
	global_store_dwordx4 v160, v[120:123], s[72:73]
	s_nop 1
	v_mul_f32_e32 v120, v125, v125
	v_mul_f32_e32 v121, v127, v127
	v_fmac_f32_e32 v120, v124, v124
	v_fmac_f32_e32 v121, v126, v126
	v_add_f32_e32 v120, v120, v121
	v_mul_f32_e32 v121, v157, v157
	v_fmac_f32_e32 v121, v156, v156
	v_add_f32_e32 v120, v121, v120
	v_mul_f32_e32 v121, v159, v159
	v_fmac_f32_e32 v121, v158, v158
	v_add_f32_e32 v124, v121, v120
	s_waitcnt vmcnt(15)
	v_mov_b32_e32 v120, v176
	v_mov_b32_e32 v121, v177
	v_mov_b32_e32 v122, v178
	v_mov_b32_e32 v123, v179
	v_lshlrev_b32_e32 v125, 16, v120
	v_and_b32_e32 v120, 0xffff0000, v120
	v_add_f32_e32 v117, v117, v120
	v_lshlrev_b32_e32 v120, 16, v121
	v_add_f32_e32 v118, v118, v120
	v_and_b32_e32 v120, 0xffff0000, v121
	v_add_f32_e32 v119, v119, v120
	v_lshlrev_b32_e32 v120, 16, v122
	v_add_f32_e32 v120, v112, v120
	v_and_b32_e32 v112, 0xffff0000, v122
	v_add_f32_e32 v121, v113, v112
	v_lshlrev_b32_e32 v112, 16, v123
	v_add_f32_e32 v122, v114, v112
	v_and_b32_e32 v112, 0xffff0000, v123
	v_add_f32_e32 v116, v116, v125
	v_add_f32_e32 v123, v115, v112
	v_cvt_pk_bf16_f32 v112, v116, v117
	v_cvt_pk_bf16_f32 v113, v118, v119
	v_cvt_pk_bf16_f32 v114, v120, v121
	v_cvt_pk_bf16_f32 v115, v122, v123
	global_store_dwordx4 v160, v[112:115], s[72:73] offset:256
	s_nop 1
	v_mul_f32_e32 v112, v117, v117
	v_mul_f32_e32 v113, v119, v119
	v_fmac_f32_e32 v112, v116, v116
	v_fmac_f32_e32 v113, v118, v118
	v_add_f32_e32 v112, v112, v113
	v_mul_f32_e32 v113, v121, v121
	v_fmac_f32_e32 v113, v120, v120
	v_add_f32_e32 v112, v113, v112
	v_mul_f32_e32 v113, v123, v123
	v_fmac_f32_e32 v113, v122, v122
	v_add_f32_e32 v112, v113, v112
	v_and_b32_e32 v114, 64, v206
	v_add_f32_e32 v113, v124, v112
	v_xor_b32_e32 v112, 16, v206
	v_add_u32_e32 v115, 64, v114
	v_cmp_lt_i32_e32 vcc, v112, v115
	s_nop 1
	v_cndmask_b32_e32 v112, v206, v112, vcc
	v_lshlrev_b32_e32 v112, 2, v112
	ds_bpermute_b32 v114, v112, v113
	s_waitcnt lgkmcnt(0)
	v_add_f32_e32 v114, v113, v114
	v_xor_b32_e32 v113, 32, v206
	v_cmp_lt_i32_e32 vcc, v113, v115
	s_nop 1
	v_cndmask_b32_e32 v113, v206, v113, vcc
	v_lshlrev_b32_e32 v113, 2, v113
	ds_bpermute_b32 v115, v113, v114
	s_and_saveexec_b64 s[24:25], s[38:39]
	s_cbranch_execz .LBB0_1064
	v_lshlrev_b32_e32 v116, 6, v154
	s_waitcnt lgkmcnt(0)
	v_add_f32_e32 v114, v114, v115
	global_store_dword v116, v114, s[54:55]
; __device__ __forceinline__ unsigned cvt_pk_bf16(float lo, float hi) { unsigned r; asm volatile("v_cvt_pk_bf16_f32 %0, %1, %2" : "=v"(r) : "v"(lo), "v"(hi)); return r; }
;     __device__ __forceinline__ void operator()(const f32x4 (&acc)[2][2][4][2], const Unit& u, int wr, int wc, int fr, int fq) const {
;     ...
;                 const unsigned row = row0 + ai * HALF + m * 16;
;                 const unsigned hoff = (row * 1024u + col0) * 2u;
;                 float sq = 0.f;
; #pragma unroll
;                 for (int bj = 0; bj < 2; ++bj) {
;                     const u32x4 xw = *(const u32x4*)(xbp + hoff + bj * (HALF * 2));
;                     f32x4 v0, v1;
;                     v0[0] = __uint_as_float(xw.x << 16) + acc[ai][bj][m][0][0]; v0[1] = __uint_as_float(xw.x & 0xffff0000u) + acc[ai][bj][m][0][1];
;                     v0[2] = __uint_as_float(xw.y << 16) + acc[ai][bj][m][0][2]; v0[3] = __uint_as_float(xw.y & 0xffff0000u) + acc[ai][bj][m][0][3];
;                     v1[0] = __uint_as_float(xw.z << 16) + acc[ai][bj][m][1][0]; v1[1] = __uint_as_float(xw.z & 0xffff0000u) + acc[ai][bj][m][1][1];
;                     v1[2] = __uint_as_float(xw.w << 16) + acc[ai][bj][m][1][2]; v1[3] = __uint_as_float(xw.w & 0xffff0000u) + acc[ai][bj][m][1][3];
;                     if (xout) { *(f32x4*)(xo + 2u * hoff + bj * (HALF * 4)) = v0; *(f32x4*)(xo + 2u * hoff + bj * (HALF * 4) + 16) = v1; }
;                     u32x4 w; w.x = cvt_pk_bf16(v0[0], v0[1]); w.y = cvt_pk_bf16(v0[2], v0[3]); w.z = cvt_pk_bf16(v1[0], v1[1]); w.w = cvt_pk_bf16(v1[2], v1[3]);
;                     *(u32x4*)(xbp + hoff + bj * (HALF * 2)) = w;
;                     sq += (v0[0] * v0[0] + v0[1] * v0[1]) + (v0[2] * v0[2] + v0[3] * v0[3]) + (v1[0] * v1[0] + v1[1] * v1[1]) + (v1[2] * v1[2] + v1[3] * v1[3]);
;                 }
;                 sq += __shfl_xor(sq, 16); sq += __shfl_xor(sq, 32);
;                 if (fq == 0) *(float*)(ssp + row * 64u + ssoff) = sq;
.LBB0_1064:
	s_or_b64 exec, exec, s[24:25]
	v_or_b32_e32 v114, 16, v154
	s_waitcnt lgkmcnt(0)
	v_lshl_add_u32 v115, v114, 11, v155
	s_waitcnt vmcnt(16)
	v_mov_b32_e32 v116, v180
	v_mov_b32_e32 v117, v181
	v_mov_b32_e32 v118, v182
	v_mov_b32_e32 v119, v183
	v_lshlrev_b32_e32 v120, 16, v116
	v_and_b32_e32 v116, 0xffff0000, v116
	v_add_f32_e32 v109, v109, v116
	v_lshlrev_b32_e32 v116, 16, v117
	v_add_f32_e32 v110, v110, v116
	v_and_b32_e32 v116, 0xffff0000, v117
	v_add_f32_e32 v111, v111, v116
	v_lshlrev_b32_e32 v116, 16, v118
	v_add_f32_e32 v116, v104, v116
	v_and_b32_e32 v104, 0xffff0000, v118
	v_add_f32_e32 v117, v105, v104
	v_lshlrev_b32_e32 v104, 16, v119
	v_add_f32_e32 v118, v106, v104
	v_and_b32_e32 v104, 0xffff0000, v119
	v_add_f32_e32 v108, v108, v120
	v_add_f32_e32 v119, v107, v104
	v_cvt_pk_bf16_f32 v104, v108, v109
	v_cvt_pk_bf16_f32 v105, v110, v111
	v_cvt_pk_bf16_f32 v106, v116, v117
	v_cvt_pk_bf16_f32 v107, v118, v119
	global_store_dwordx4 v115, v[104:107], s[72:73]
	s_nop 1
	v_mul_f32_e32 v104, v109, v109
	v_mul_f32_e32 v105, v111, v111
	v_fmac_f32_e32 v104, v108, v108
	v_fmac_f32_e32 v105, v110, v110
	v_add_f32_e32 v104, v104, v105
	v_mul_f32_e32 v105, v117, v117
	v_fmac_f32_e32 v105, v116, v116
	v_add_f32_e32 v104, v105, v104
	v_mul_f32_e32 v105, v119, v119
	v_fmac_f32_e32 v105, v118, v118
	v_add_f32_e32 v108, v105, v104
	s_waitcnt vmcnt(16)
	v_mov_b32_e32 v104, v184
	v_mov_b32_e32 v105, v185
	v_mov_b32_e32 v106, v186
	v_mov_b32_e32 v107, v187
	v_lshlrev_b32_e32 v109, 16, v104
	v_and_b32_e32 v104, 0xffff0000, v104
	v_add_f32_e32 v101, v101, v104
	v_lshlrev_b32_e32 v104, 16, v105
	v_add_f32_e32 v102, v102, v104
	v_and_b32_e32 v104, 0xffff0000, v105
	v_add_f32_e32 v103, v103, v104
	v_lshlrev_b32_e32 v104, 16, v106
	v_add_f32_e32 v104, v96, v104
	v_and_b32_e32 v96, 0xffff0000, v106
	v_add_f32_e32 v105, v97, v96
	v_lshlrev_b32_e32 v96, 16, v107
	v_add_f32_e32 v106, v98, v96
	v_and_b32_e32 v96, 0xffff0000, v107
	v_add_f32_e32 v100, v100, v109
	v_add_f32_e32 v107, v99, v96
	v_cvt_pk_bf16_f32 v96, v100, v101
	v_cvt_pk_bf16_f32 v97, v102, v103
	v_cvt_pk_bf16_f32 v98, v104, v105
	v_cvt_pk_bf16_f32 v99, v106, v107
	global_store_dwordx4 v115, v[96:99], s[72:73] offset:256
	s_nop 1
	v_mul_f32_e32 v96, v101, v101
	v_mul_f32_e32 v97, v103, v103
	v_fmac_f32_e32 v96, v100, v100
	v_fmac_f32_e32 v97, v102, v102
	v_add_f32_e32 v96, v96, v97
	v_mul_f32_e32 v97, v105, v105
	v_fmac_f32_e32 v97, v104, v104
	v_add_f32_e32 v96, v97, v96
	v_mul_f32_e32 v97, v107, v107
	v_fmac_f32_e32 v97, v106, v106
	v_add_f32_e32 v96, v97, v96
	v_add_f32_e32 v96, v108, v96
	ds_bpermute_b32 v97, v112, v96
	s_waitcnt lgkmcnt(0)
	v_add_f32_e32 v96, v96, v97
	ds_bpermute_b32 v97, v113, v96
	s_and_saveexec_b64 s[24:25], s[38:39]
	s_cbranch_execz .LBB0_1066
	v_lshlrev_b32_e32 v98, 6, v114
	s_waitcnt lgkmcnt(0)
	v_add_f32_e32 v96, v96, v97
	global_store_dword v98, v96, s[54:55]
.LBB0_1066:
	s_or_b64 exec, exec, s[24:25]
	v_or_b32_e32 v96, 32, v154
	s_waitcnt lgkmcnt(0)
	v_lshl_add_u32 v97, v96, 11, v155
	s_waitcnt vmcnt(17)
	v_mov_b32_e32 v98, v188
	v_mov_b32_e32 v99, v189
	v_mov_b32_e32 v100, v190
	v_mov_b32_e32 v101, v191
	v_lshlrev_b32_e32 v102, 16, v98
	v_and_b32_e32 v98, 0xffff0000, v98
	v_add_f32_e32 v93, v93, v98
	v_lshlrev_b32_e32 v98, 16, v99
	v_add_f32_e32 v94, v94, v98
	v_and_b32_e32 v98, 0xffff0000, v99
	v_add_f32_e32 v95, v95, v98
	v_lshlrev_b32_e32 v98, 16, v100
	v_add_f32_e32 v98, v88, v98
	v_and_b32_e32 v88, 0xffff0000, v100
	v_add_f32_e32 v99, v89, v88
	v_lshlrev_b32_e32 v88, 16, v101
	v_add_f32_e32 v100, v90, v88
	v_and_b32_e32 v88, 0xffff0000, v101
	v_add_f32_e32 v92, v92, v102
	v_add_f32_e32 v101, v91, v88
	v_cvt_pk_bf16_f32 v88, v92, v93
	v_cvt_pk_bf16_f32 v89, v94, v95
	v_cvt_pk_bf16_f32 v90, v98, v99
	v_cvt_pk_bf16_f32 v91, v100, v101
	global_store_dwordx4 v97, v[88:91], s[72:73]
	s_nop 1
	v_mul_f32_e32 v88, v93, v93
	v_mul_f32_e32 v89, v95, v95
	v_fmac_f32_e32 v88, v92, v92
	v_fmac_f32_e32 v89, v94, v94
	v_add_f32_e32 v88, v88, v89
	v_mul_f32_e32 v89, v99, v99
	v_fmac_f32_e32 v89, v98, v98
	v_add_f32_e32 v88, v89, v88
	v_mul_f32_e32 v89, v101, v101
	v_fmac_f32_e32 v89, v100, v100
	v_add_f32_e32 v92, v89, v88
	s_waitcnt vmcnt(17)
	v_mov_b32_e32 v88, v192
	v_mov_b32_e32 v89, v193
	v_mov_b32_e32 v90, v194
	v_mov_b32_e32 v91, v195
	v_lshlrev_b32_e32 v93, 16, v88
	v_and_b32_e32 v88, 0xffff0000, v88
	v_add_f32_e32 v85, v85, v88
	v_lshlrev_b32_e32 v88, 16, v89
	v_add_f32_e32 v86, v86, v88
	v_and_b32_e32 v88, 0xffff0000, v89
	v_add_f32_e32 v87, v87, v88
	v_lshlrev_b32_e32 v88, 16, v90
	v_add_f32_e32 v88, v80, v88
	v_and_b32_e32 v80, 0xffff0000, v90
	v_add_f32_e32 v89, v81, v80
	v_lshlrev_b32_e32 v80, 16, v91
	v_add_f32_e32 v90, v82, v80
	v_and_b32_e32 v80, 0xffff0000, v91
	v_add_f32_e32 v84, v84, v93
	v_add_f32_e32 v91, v83, v80
	v_cvt_pk_bf16_f32 v80, v84, v85
	v_cvt_pk_bf16_f32 v81, v86, v87
	v_cvt_pk_bf16_f32 v82, v88, v89
	v_cvt_pk_bf16_f32 v83, v90, v91
	global_store_dwordx4 v97, v[80:83], s[72:73] offset:256
	s_nop 1
	v_mul_f32_e32 v80, v85, v85
	v_mul_f32_e32 v81, v87, v87
	v_fmac_f32_e32 v80, v84, v84
	v_fmac_f32_e32 v81, v86, v86
	v_add_f32_e32 v80, v80, v81
	v_mul_f32_e32 v81, v89, v89
	v_fmac_f32_e32 v81, v88, v88
	v_add_f32_e32 v80, v81, v80
	v_mul_f32_e32 v81, v91, v91
	v_fmac_f32_e32 v81, v90, v90
	v_add_f32_e32 v80, v81, v80
	v_add_f32_e32 v80, v92, v80
	ds_bpermute_b32 v81, v112, v80
	s_waitcnt lgkmcnt(0)
	v_add_f32_e32 v80, v80, v81
	ds_bpermute_b32 v81, v113, v80
	s_and_saveexec_b64 s[24:25], s[38:39]
	v_readlane_b32 s96, v250, 25
	v_readlane_b32 s97, v250, 26
	s_cbranch_execz .LBB0_1068
	v_lshlrev_b32_e32 v82, 6, v96
	s_waitcnt lgkmcnt(0)
	v_add_f32_e32 v80, v80, v81
	global_store_dword v82, v80, s[54:55]
; __device__ __forceinline__ unsigned cvt_pk_bf16(float lo, float hi) { unsigned r; asm volatile("v_cvt_pk_bf16_f32 %0, %1, %2" : "=v"(r) : "v"(lo), "v"(hi)); return r; }
;     __device__ __forceinline__ void operator()(const f32x4 (&acc)[2][2][4][2], const Unit& u, int wr, int wc, int fr, int fq) const {
;     ...
;                 const unsigned row = row0 + ai * HALF + m * 16;
;                 const unsigned hoff = (row * 1024u + col0) * 2u;
;                 float sq = 0.f;
; #pragma unroll
;                 for (int bj = 0; bj < 2; ++bj) {
;                     const u32x4 xw = *(const u32x4*)(xbp + hoff + bj * (HALF * 2));
;                     f32x4 v0, v1;
;                     v0[0] = __uint_as_float(xw.x << 16) + acc[ai][bj][m][0][0]; v0[1] = __uint_as_float(xw.x & 0xffff0000u) + acc[ai][bj][m][0][1];
;                     v0[2] = __uint_as_float(xw.y << 16) + acc[ai][bj][m][0][2]; v0[3] = __uint_as_float(xw.y & 0xffff0000u) + acc[ai][bj][m][0][3];
;                     v1[0] = __uint_as_float(xw.z << 16) + acc[ai][bj][m][1][0]; v1[1] = __uint_as_float(xw.z & 0xffff0000u) + acc[ai][bj][m][1][1];
;                     v1[2] = __uint_as_float(xw.w << 16) + acc[ai][bj][m][1][2]; v1[3] = __uint_as_float(xw.w & 0xffff0000u) + acc[ai][bj][m][1][3];
;                     if (xout) { *(f32x4*)(xo + 2u * hoff + bj * (HALF * 4)) = v0; *(f32x4*)(xo + 2u * hoff + bj * (HALF * 4) + 16) = v1; }
;                     u32x4 w; w.x = cvt_pk_bf16(v0[0], v0[1]); w.y = cvt_pk_bf16(v0[2], v0[3]); w.z = cvt_pk_bf16(v1[0], v1[1]); w.w = cvt_pk_bf16(v1[2], v1[3]);
;                     *(u32x4*)(xbp + hoff + bj * (HALF * 2)) = w;
;                     sq += (v0[0] * v0[0] + v0[1] * v0[1]) + (v0[2] * v0[2] + v0[3] * v0[3]) + (v1[0] * v1[0] + v1[1] * v1[1]) + (v1[2] * v1[2] + v1[3] * v1[3]);
;                 }
;                 sq += __shfl_xor(sq, 16); sq += __shfl_xor(sq, 32);
;                 if (fq == 0) *(float*)(ssp + row * 64u + ssoff) = sq;
.LBB0_1068:
	s_or_b64 exec, exec, s[24:25]
	v_or_b32_e32 v80, 48, v154
	s_waitcnt lgkmcnt(0)
	v_lshl_add_u32 v81, v80, 11, v155
	s_waitcnt vmcnt(18)
	v_mov_b32_e32 v82, v196
	v_mov_b32_e32 v83, v197
	v_mov_b32_e32 v84, v198
	v_mov_b32_e32 v85, v199
	v_lshlrev_b32_e32 v86, 16, v82
	v_and_b32_e32 v82, 0xffff0000, v82
	v_add_f32_e32 v77, v77, v82
	v_lshlrev_b32_e32 v82, 16, v83
	v_add_f32_e32 v78, v78, v82
	v_and_b32_e32 v82, 0xffff0000, v83
	v_add_f32_e32 v79, v79, v82
	v_lshlrev_b32_e32 v82, 16, v84
	v_add_f32_e32 v82, v72, v82
	v_and_b32_e32 v72, 0xffff0000, v84
	v_add_f32_e32 v83, v73, v72
	v_lshlrev_b32_e32 v72, 16, v85
	v_add_f32_e32 v84, v74, v72
	v_and_b32_e32 v72, 0xffff0000, v85
	v_add_f32_e32 v76, v76, v86
	v_add_f32_e32 v85, v75, v72
	v_cvt_pk_bf16_f32 v72, v76, v77
	v_cvt_pk_bf16_f32 v73, v78, v79
	v_cvt_pk_bf16_f32 v74, v82, v83
	v_cvt_pk_bf16_f32 v75, v84, v85
	global_store_dwordx4 v81, v[72:75], s[72:73]
	s_nop 1
	v_mul_f32_e32 v72, v77, v77
	v_mul_f32_e32 v73, v79, v79
	v_fmac_f32_e32 v72, v76, v76
	v_fmac_f32_e32 v73, v78, v78
	v_add_f32_e32 v72, v72, v73
	v_mul_f32_e32 v73, v83, v83
	v_fmac_f32_e32 v73, v82, v82
	v_add_f32_e32 v72, v73, v72
	v_mul_f32_e32 v73, v85, v85
	v_fmac_f32_e32 v73, v84, v84
	v_add_f32_e32 v76, v73, v72
	s_waitcnt vmcnt(18)
	v_mov_b32_e32 v72, v200
	v_mov_b32_e32 v73, v201
	v_mov_b32_e32 v74, v202
	v_mov_b32_e32 v75, v203
	v_lshlrev_b32_e32 v77, 16, v72
	v_and_b32_e32 v72, 0xffff0000, v72
	v_add_f32_e32 v69, v69, v72
	v_lshlrev_b32_e32 v72, 16, v73
	v_add_f32_e32 v70, v70, v72
	v_and_b32_e32 v72, 0xffff0000, v73
	v_add_f32_e32 v71, v71, v72
	v_lshlrev_b32_e32 v72, 16, v74
	v_add_f32_e32 v72, v64, v72
	v_and_b32_e32 v64, 0xffff0000, v74
	v_add_f32_e32 v73, v65, v64
	v_lshlrev_b32_e32 v64, 16, v75
	v_add_f32_e32 v74, v66, v64
	v_and_b32_e32 v64, 0xffff0000, v75
	v_add_f32_e32 v68, v68, v77
	v_add_f32_e32 v75, v67, v64
	v_cvt_pk_bf16_f32 v64, v68, v69
	v_cvt_pk_bf16_f32 v65, v70, v71
	v_cvt_pk_bf16_f32 v66, v72, v73
	v_cvt_pk_bf16_f32 v67, v74, v75
	global_store_dwordx4 v81, v[64:67], s[72:73] offset:256
	s_nop 1
	v_mul_f32_e32 v64, v69, v69
	v_mul_f32_e32 v65, v71, v71
	v_fmac_f32_e32 v64, v68, v68
	v_fmac_f32_e32 v65, v70, v70
	v_add_f32_e32 v64, v64, v65
	v_mul_f32_e32 v65, v73, v73
	v_fmac_f32_e32 v65, v72, v72
	v_add_f32_e32 v64, v65, v64
	v_mul_f32_e32 v65, v75, v75
	v_fmac_f32_e32 v65, v74, v74
	v_add_f32_e32 v64, v65, v64
	v_add_f32_e32 v64, v76, v64
	ds_bpermute_b32 v65, v112, v64
	s_waitcnt lgkmcnt(0)
	v_add_f32_e32 v64, v64, v65
	ds_bpermute_b32 v65, v113, v64
	s_and_saveexec_b64 s[24:25], s[38:39]
	s_cbranch_execz .LBB0_1070
	v_lshlrev_b32_e32 v66, 6, v80
	s_waitcnt lgkmcnt(0)
	v_add_f32_e32 v64, v64, v65
	global_store_dword v66, v64, s[54:55]
.LBB0_1070:
	s_or_b64 exec, exec, s[24:25]
	v_add_u32_e32 v64, 0x80, v154
	s_waitcnt lgkmcnt(0)
	v_lshl_add_u32 v65, v64, 11, v155
	s_waitcnt vmcnt(19)
	v_mov_b32_e32 v66, v208
	v_mov_b32_e32 v67, v209
	v_mov_b32_e32 v68, v210
	v_mov_b32_e32 v69, v211
	v_lshlrev_b32_e32 v70, 16, v66
	v_and_b32_e32 v66, 0xffff0000, v66
	v_add_f32_e32 v61, v61, v66
	v_lshlrev_b32_e32 v66, 16, v67
	v_add_f32_e32 v62, v62, v66
	v_and_b32_e32 v66, 0xffff0000, v67
	v_add_f32_e32 v63, v63, v66
	v_lshlrev_b32_e32 v66, 16, v68
	v_add_f32_e32 v66, v56, v66
	v_and_b32_e32 v56, 0xffff0000, v68
	v_add_f32_e32 v67, v57, v56
	v_lshlrev_b32_e32 v56, 16, v69
	v_add_f32_e32 v68, v58, v56
	v_and_b32_e32 v56, 0xffff0000, v69
	v_add_f32_e32 v60, v60, v70
	v_add_f32_e32 v69, v59, v56
	v_cvt_pk_bf16_f32 v56, v60, v61
	v_cvt_pk_bf16_f32 v57, v62, v63
	v_cvt_pk_bf16_f32 v58, v66, v67
	v_cvt_pk_bf16_f32 v59, v68, v69
	global_store_dwordx4 v65, v[56:59], s[72:73]
	s_nop 1
	v_mul_f32_e32 v56, v61, v61
	v_mul_f32_e32 v57, v63, v63
	v_fmac_f32_e32 v56, v60, v60
	v_fmac_f32_e32 v57, v62, v62
	v_add_f32_e32 v56, v56, v57
	v_mul_f32_e32 v57, v67, v67
	v_fmac_f32_e32 v57, v66, v66
	v_add_f32_e32 v56, v57, v56
	v_mul_f32_e32 v57, v69, v69
	v_fmac_f32_e32 v57, v68, v68
	v_add_f32_e32 v60, v57, v56
	s_waitcnt vmcnt(19)
	v_mov_b32_e32 v56, v212
	v_mov_b32_e32 v57, v213
	v_mov_b32_e32 v58, v214
	v_mov_b32_e32 v59, v215
	v_lshlrev_b32_e32 v61, 16, v56
	v_and_b32_e32 v56, 0xffff0000, v56
	v_add_f32_e32 v53, v53, v56
	v_lshlrev_b32_e32 v56, 16, v57
	v_add_f32_e32 v54, v54, v56
	v_and_b32_e32 v56, 0xffff0000, v57
	v_add_f32_e32 v55, v55, v56
	v_lshlrev_b32_e32 v56, 16, v58
	v_add_f32_e32 v56, v48, v56
	v_and_b32_e32 v48, 0xffff0000, v58
	v_add_f32_e32 v57, v49, v48
	v_lshlrev_b32_e32 v48, 16, v59
	v_add_f32_e32 v58, v50, v48
	v_and_b32_e32 v48, 0xffff0000, v59
	v_add_f32_e32 v52, v52, v61
	v_add_f32_e32 v59, v51, v48
	v_cvt_pk_bf16_f32 v48, v52, v53
	v_cvt_pk_bf16_f32 v49, v54, v55
	v_cvt_pk_bf16_f32 v50, v56, v57
	v_cvt_pk_bf16_f32 v51, v58, v59
	global_store_dwordx4 v65, v[48:51], s[72:73] offset:256
	s_nop 1
	v_mul_f32_e32 v48, v53, v53
	v_mul_f32_e32 v49, v55, v55
	v_fmac_f32_e32 v48, v52, v52
	v_fmac_f32_e32 v49, v54, v54
	v_add_f32_e32 v48, v48, v49
	v_mul_f32_e32 v49, v57, v57
	v_fmac_f32_e32 v49, v56, v56
	v_add_f32_e32 v48, v49, v48
	v_mul_f32_e32 v49, v59, v59
	v_fmac_f32_e32 v49, v58, v58
	v_add_f32_e32 v48, v49, v48
	v_add_f32_e32 v48, v60, v48
	ds_bpermute_b32 v49, v112, v48
	s_waitcnt lgkmcnt(0)
	v_add_f32_e32 v48, v48, v49
	ds_bpermute_b32 v49, v113, v48
	s_and_saveexec_b64 s[24:25], s[38:39]
	s_cbranch_execz .LBB0_1072
	v_lshlrev_b32_e32 v50, 6, v64
	s_waitcnt lgkmcnt(0)
	v_add_f32_e32 v48, v48, v49
	global_store_dword v50, v48, s[54:55]
; __device__ __forceinline__ unsigned cvt_pk_bf16(float lo, float hi) { unsigned r; asm volatile("v_cvt_pk_bf16_f32 %0, %1, %2" : "=v"(r) : "v"(lo), "v"(hi)); return r; }
;     __device__ __forceinline__ void operator()(const f32x4 (&acc)[2][2][4][2], const Unit& u, int wr, int wc, int fr, int fq) const {
;     ...
;                 const unsigned row = row0 + ai * HALF + m * 16;
;                 const unsigned hoff = (row * 1024u + col0) * 2u;
;                 float sq = 0.f;
; #pragma unroll
;                 for (int bj = 0; bj < 2; ++bj) {
;                     const u32x4 xw = *(const u32x4*)(xbp + hoff + bj * (HALF * 2));
;                     f32x4 v0, v1;
;                     v0[0] = __uint_as_float(xw.x << 16) + acc[ai][bj][m][0][0]; v0[1] = __uint_as_float(xw.x & 0xffff0000u) + acc[ai][bj][m][0][1];
;                     v0[2] = __uint_as_float(xw.y << 16) + acc[ai][bj][m][0][2]; v0[3] = __uint_as_float(xw.y & 0xffff0000u) + acc[ai][bj][m][0][3];
;                     v1[0] = __uint_as_float(xw.z << 16) + acc[ai][bj][m][1][0]; v1[1] = __uint_as_float(xw.z & 0xffff0000u) + acc[ai][bj][m][1][1];
;                     v1[2] = __uint_as_float(xw.w << 16) + acc[ai][bj][m][1][2]; v1[3] = __uint_as_float(xw.w & 0xffff0000u) + acc[ai][bj][m][1][3];
;                     if (xout) { *(f32x4*)(xo + 2u * hoff + bj * (HALF * 4)) = v0; *(f32x4*)(xo + 2u * hoff + bj * (HALF * 4) + 16) = v1; }
;                     u32x4 w; w.x = cvt_pk_bf16(v0[0], v0[1]); w.y = cvt_pk_bf16(v0[2], v0[3]); w.z = cvt_pk_bf16(v1[0], v1[1]); w.w = cvt_pk_bf16(v1[2], v1[3]);
;                     *(u32x4*)(xbp + hoff + bj * (HALF * 2)) = w;
;                     sq += (v0[0] * v0[0] + v0[1] * v0[1]) + (v0[2] * v0[2] + v0[3] * v0[3]) + (v1[0] * v1[0] + v1[1] * v1[1]) + (v1[2] * v1[2] + v1[3] * v1[3]);
;                 }
;                 sq += __shfl_xor(sq, 16); sq += __shfl_xor(sq, 32);
;                 if (fq == 0) *(float*)(ssp + row * 64u + ssoff) = sq;
.LBB0_1072:
	s_or_b64 exec, exec, s[24:25]
	v_add_u32_e32 v48, 0x90, v154
	s_waitcnt lgkmcnt(0)
	v_lshl_add_u32 v49, v48, 11, v155
	s_waitcnt vmcnt(20)
	v_mov_b32_e32 v50, v216
	v_mov_b32_e32 v51, v217
	v_mov_b32_e32 v52, v218
	v_mov_b32_e32 v53, v219
	v_lshlrev_b32_e32 v54, 16, v50
	v_and_b32_e32 v50, 0xffff0000, v50
	v_add_f32_e32 v45, v45, v50
	v_lshlrev_b32_e32 v50, 16, v51
	v_add_f32_e32 v46, v46, v50
	v_and_b32_e32 v50, 0xffff0000, v51
	v_add_f32_e32 v47, v47, v50
	v_lshlrev_b32_e32 v50, 16, v52
	v_add_f32_e32 v50, v40, v50
	v_and_b32_e32 v40, 0xffff0000, v52
	v_add_f32_e32 v51, v41, v40
	v_lshlrev_b32_e32 v40, 16, v53
	v_add_f32_e32 v52, v42, v40
	v_and_b32_e32 v40, 0xffff0000, v53
	v_add_f32_e32 v44, v44, v54
	v_add_f32_e32 v53, v43, v40
	v_cvt_pk_bf16_f32 v40, v44, v45
	v_cvt_pk_bf16_f32 v41, v46, v47
	v_cvt_pk_bf16_f32 v42, v50, v51
	v_cvt_pk_bf16_f32 v43, v52, v53
	global_store_dwordx4 v49, v[40:43], s[72:73]
	s_nop 1
	v_mul_f32_e32 v40, v45, v45
	v_mul_f32_e32 v41, v47, v47
	v_fmac_f32_e32 v40, v44, v44
	v_fmac_f32_e32 v41, v46, v46
	v_add_f32_e32 v40, v40, v41
	v_mul_f32_e32 v41, v51, v51
	v_fmac_f32_e32 v41, v50, v50
	v_add_f32_e32 v40, v41, v40
	v_mul_f32_e32 v41, v53, v53
	v_fmac_f32_e32 v41, v52, v52
	v_add_f32_e32 v44, v41, v40
	s_waitcnt vmcnt(20)
	v_mov_b32_e32 v40, v220
	v_mov_b32_e32 v41, v221
	v_mov_b32_e32 v42, v222
	v_mov_b32_e32 v43, v223
	v_lshlrev_b32_e32 v45, 16, v40
	v_and_b32_e32 v40, 0xffff0000, v40
	v_add_f32_e32 v37, v37, v40
	v_lshlrev_b32_e32 v40, 16, v41
	v_add_f32_e32 v38, v38, v40
	v_and_b32_e32 v40, 0xffff0000, v41
	v_add_f32_e32 v39, v39, v40
	v_lshlrev_b32_e32 v40, 16, v42
	v_add_f32_e32 v40, v32, v40
	v_and_b32_e32 v32, 0xffff0000, v42
	v_add_f32_e32 v41, v33, v32
	v_lshlrev_b32_e32 v32, 16, v43
	v_add_f32_e32 v42, v34, v32
	v_and_b32_e32 v32, 0xffff0000, v43
	v_add_f32_e32 v36, v36, v45
	v_add_f32_e32 v43, v35, v32
	v_cvt_pk_bf16_f32 v32, v36, v37
	v_cvt_pk_bf16_f32 v33, v38, v39
	v_cvt_pk_bf16_f32 v34, v40, v41
	v_cvt_pk_bf16_f32 v35, v42, v43
	global_store_dwordx4 v49, v[32:35], s[72:73] offset:256
	s_nop 1
	v_mul_f32_e32 v32, v37, v37
	v_mul_f32_e32 v33, v39, v39
	v_fmac_f32_e32 v32, v36, v36
	v_fmac_f32_e32 v33, v38, v38
	v_add_f32_e32 v32, v32, v33
	v_mul_f32_e32 v33, v41, v41
	v_fmac_f32_e32 v33, v40, v40
	v_add_f32_e32 v32, v33, v32
	v_mul_f32_e32 v33, v43, v43
	v_fmac_f32_e32 v33, v42, v42
	v_add_f32_e32 v32, v33, v32
	v_add_f32_e32 v32, v44, v32
	ds_bpermute_b32 v33, v112, v32
	s_waitcnt lgkmcnt(0)
	v_add_f32_e32 v32, v32, v33
	ds_bpermute_b32 v33, v113, v32
	s_and_saveexec_b64 s[24:25], s[38:39]
	s_cbranch_execz .LBB0_1074
	v_lshlrev_b32_e32 v34, 6, v48
	s_waitcnt lgkmcnt(0)
	v_add_f32_e32 v32, v32, v33
	global_store_dword v34, v32, s[54:55]
; __device__ __forceinline__ unsigned cvt_pk_bf16(float lo, float hi) { unsigned r; asm volatile("v_cvt_pk_bf16_f32 %0, %1, %2" : "=v"(r) : "v"(lo), "v"(hi)); return r; }
;     __device__ __forceinline__ void operator()(const f32x4 (&acc)[2][2][4][2], const Unit& u, int wr, int wc, int fr, int fq) const {
;     ...
;                 const unsigned row = row0 + ai * HALF + m * 16;
;                 const unsigned hoff = (row * 1024u + col0) * 2u;
;                 float sq = 0.f;
; #pragma unroll
;                 for (int bj = 0; bj < 2; ++bj) {
;                     const u32x4 xw = *(const u32x4*)(xbp + hoff + bj * (HALF * 2));
;                     f32x4 v0, v1;
;                     v0[0] = __uint_as_float(xw.x << 16) + acc[ai][bj][m][0][0]; v0[1] = __uint_as_float(xw.x & 0xffff0000u) + acc[ai][bj][m][0][1];
;                     v0[2] = __uint_as_float(xw.y << 16) + acc[ai][bj][m][0][2]; v0[3] = __uint_as_float(xw.y & 0xffff0000u) + acc[ai][bj][m][0][3];
;                     v1[0] = __uint_as_float(xw.z << 16) + acc[ai][bj][m][1][0]; v1[1] = __uint_as_float(xw.z & 0xffff0000u) + acc[ai][bj][m][1][1];
;                     v1[2] = __uint_as_float(xw.w << 16) + acc[ai][bj][m][1][2]; v1[3] = __uint_as_float(xw.w & 0xffff0000u) + acc[ai][bj][m][1][3];
;                     if (xout) { *(f32x4*)(xo + 2u * hoff + bj * (HALF * 4)) = v0; *(f32x4*)(xo + 2u * hoff + bj * (HALF * 4) + 16) = v1; }
;                     u32x4 w; w.x = cvt_pk_bf16(v0[0], v0[1]); w.y = cvt_pk_bf16(v0[2], v0[3]); w.z = cvt_pk_bf16(v1[0], v1[1]); w.w = cvt_pk_bf16(v1[2], v1[3]);
;                     *(u32x4*)(xbp + hoff + bj * (HALF * 2)) = w;
;                     sq += (v0[0] * v0[0] + v0[1] * v0[1]) + (v0[2] * v0[2] + v0[3] * v0[3]) + (v1[0] * v1[0] + v1[1] * v1[1]) + (v1[2] * v1[2] + v1[3] * v1[3]);
;                 }
;                 sq += __shfl_xor(sq, 16); sq += __shfl_xor(sq, 32);
;                 if (fq == 0) *(float*)(ssp + row * 64u + ssoff) = sq;
.LBB0_1074:
	s_or_b64 exec, exec, s[24:25]
	v_add_u32_e32 v32, 0xa0, v154
	s_waitcnt lgkmcnt(0)
	v_lshl_add_u32 v33, v32, 11, v155
	s_waitcnt vmcnt(21)
	v_mov_b32_e32 v34, v224
	v_mov_b32_e32 v35, v225
	v_mov_b32_e32 v36, v226
	v_mov_b32_e32 v37, v227
	v_lshlrev_b32_e32 v38, 16, v34
	v_and_b32_e32 v34, 0xffff0000, v34
	v_add_f32_e32 v29, v29, v34
	v_lshlrev_b32_e32 v34, 16, v35
	v_add_f32_e32 v30, v30, v34
	v_and_b32_e32 v34, 0xffff0000, v35
	v_add_f32_e32 v31, v31, v34
	v_lshlrev_b32_e32 v34, 16, v36
	v_add_f32_e32 v34, v24, v34
	v_and_b32_e32 v24, 0xffff0000, v36
	v_add_f32_e32 v35, v25, v24
	v_lshlrev_b32_e32 v24, 16, v37
	v_add_f32_e32 v36, v26, v24
	v_and_b32_e32 v24, 0xffff0000, v37
	v_add_f32_e32 v28, v28, v38
	v_add_f32_e32 v37, v27, v24
	v_cvt_pk_bf16_f32 v24, v28, v29
	v_cvt_pk_bf16_f32 v25, v30, v31
	v_cvt_pk_bf16_f32 v26, v34, v35
	v_cvt_pk_bf16_f32 v27, v36, v37
	global_store_dwordx4 v33, v[24:27], s[72:73]
	s_nop 1
	v_mul_f32_e32 v24, v29, v29
	v_mul_f32_e32 v25, v31, v31
	v_fmac_f32_e32 v24, v28, v28
	v_fmac_f32_e32 v25, v30, v30
	v_add_f32_e32 v24, v24, v25
	v_mul_f32_e32 v25, v35, v35
	v_fmac_f32_e32 v25, v34, v34
	v_add_f32_e32 v24, v25, v24
	v_mul_f32_e32 v25, v37, v37
	v_fmac_f32_e32 v25, v36, v36
	v_add_f32_e32 v28, v25, v24
	s_waitcnt vmcnt(21)
	v_mov_b32_e32 v24, v228
	v_mov_b32_e32 v25, v229
	v_mov_b32_e32 v26, v230
	v_mov_b32_e32 v27, v231
	v_lshlrev_b32_e32 v29, 16, v24
	v_and_b32_e32 v24, 0xffff0000, v24
	v_add_f32_e32 v21, v21, v24
	v_lshlrev_b32_e32 v24, 16, v25
	v_add_f32_e32 v22, v22, v24
	v_and_b32_e32 v24, 0xffff0000, v25
	v_add_f32_e32 v23, v23, v24
	v_lshlrev_b32_e32 v24, 16, v26
	v_add_f32_e32 v24, v16, v24
	v_and_b32_e32 v16, 0xffff0000, v26
	v_add_f32_e32 v25, v17, v16
	v_lshlrev_b32_e32 v16, 16, v27
	v_add_f32_e32 v26, v18, v16
	v_and_b32_e32 v16, 0xffff0000, v27
	v_add_f32_e32 v20, v20, v29
	v_add_f32_e32 v27, v19, v16
	v_cvt_pk_bf16_f32 v16, v20, v21
	v_cvt_pk_bf16_f32 v17, v22, v23
	v_cvt_pk_bf16_f32 v18, v24, v25
	v_cvt_pk_bf16_f32 v19, v26, v27
	global_store_dwordx4 v33, v[16:19], s[72:73] offset:256
	s_nop 1
	v_mul_f32_e32 v16, v21, v21
	v_mul_f32_e32 v17, v23, v23
	v_fmac_f32_e32 v16, v20, v20
	v_fmac_f32_e32 v17, v22, v22
	v_add_f32_e32 v16, v16, v17
	v_mul_f32_e32 v17, v25, v25
	v_fmac_f32_e32 v17, v24, v24
	v_add_f32_e32 v16, v17, v16
	v_mul_f32_e32 v17, v27, v27
	v_fmac_f32_e32 v17, v26, v26
	v_add_f32_e32 v16, v17, v16
	v_add_f32_e32 v16, v28, v16
	ds_bpermute_b32 v17, v112, v16
	s_waitcnt lgkmcnt(0)
	v_add_f32_e32 v16, v16, v17
	ds_bpermute_b32 v17, v113, v16
	s_and_saveexec_b64 s[24:25], s[38:39]
	s_cbranch_execz .LBB0_1076
	v_lshlrev_b32_e32 v18, 6, v32
	s_waitcnt lgkmcnt(0)
	v_add_f32_e32 v16, v16, v17
	global_store_dword v18, v16, s[54:55]
.LBB0_1076:
	s_or_b64 exec, exec, s[24:25]
	v_add_u32_e32 v16, 0xb0, v154
	s_waitcnt lgkmcnt(0)
	v_lshl_add_u32 v17, v16, 11, v155
	s_waitcnt vmcnt(22)
	v_mov_b32_e32 v18, v232
	v_mov_b32_e32 v19, v233
	v_mov_b32_e32 v20, v234
	v_mov_b32_e32 v21, v235
	v_lshlrev_b32_e32 v22, 16, v18
	v_and_b32_e32 v18, 0xffff0000, v18
	v_add_f32_e32 v13, v13, v18
	v_lshlrev_b32_e32 v18, 16, v19
	v_add_f32_e32 v14, v14, v18
	v_and_b32_e32 v18, 0xffff0000, v19
	v_add_f32_e32 v15, v15, v18
	v_lshlrev_b32_e32 v18, 16, v20
	v_add_f32_e32 v18, v8, v18
	v_and_b32_e32 v8, 0xffff0000, v20
	v_add_f32_e32 v19, v9, v8
	v_lshlrev_b32_e32 v8, 16, v21
	v_add_f32_e32 v20, v10, v8
	v_and_b32_e32 v8, 0xffff0000, v21
	v_add_f32_e32 v12, v12, v22
	v_add_f32_e32 v21, v11, v8
	v_cvt_pk_bf16_f32 v8, v12, v13
	v_cvt_pk_bf16_f32 v9, v14, v15
	v_cvt_pk_bf16_f32 v10, v18, v19
	v_cvt_pk_bf16_f32 v11, v20, v21
	global_store_dwordx4 v17, v[8:11], s[72:73]
	s_nop 1
	v_mul_f32_e32 v8, v13, v13
	v_mul_f32_e32 v9, v15, v15
	v_fmac_f32_e32 v8, v12, v12
	v_fmac_f32_e32 v9, v14, v14
	v_add_f32_e32 v8, v8, v9
	v_mul_f32_e32 v9, v19, v19
	v_fmac_f32_e32 v9, v18, v18
	v_add_f32_e32 v8, v9, v8
	v_mul_f32_e32 v9, v21, v21
	v_fmac_f32_e32 v9, v20, v20
	v_add_f32_e32 v12, v9, v8
	s_waitcnt vmcnt(22)
	v_mov_b32_e32 v8, v236
	v_mov_b32_e32 v9, v237
	v_mov_b32_e32 v10, v238
	v_mov_b32_e32 v11, v239
	v_lshlrev_b32_e32 v13, 16, v8
	v_and_b32_e32 v8, 0xffff0000, v8
	v_add_f32_e32 v5, v5, v8
	v_lshlrev_b32_e32 v8, 16, v9
	v_add_f32_e32 v6, v6, v8
	v_and_b32_e32 v8, 0xffff0000, v9
	v_add_f32_e32 v7, v7, v8
	v_lshlrev_b32_e32 v8, 16, v10
	v_add_f32_e32 v8, v0, v8
	v_and_b32_e32 v0, 0xffff0000, v10
	v_add_f32_e32 v9, v1, v0
	v_lshlrev_b32_e32 v0, 16, v11
	v_add_f32_e32 v10, v2, v0
	v_and_b32_e32 v0, 0xffff0000, v11
	v_add_f32_e32 v4, v4, v13
	v_add_f32_e32 v11, v3, v0
	v_cvt_pk_bf16_f32 v0, v4, v5
	v_cvt_pk_bf16_f32 v1, v6, v7
	v_cvt_pk_bf16_f32 v2, v8, v9
	v_cvt_pk_bf16_f32 v3, v10, v11
	global_store_dwordx4 v17, v[0:3], s[72:73] offset:256
	s_nop 1
	v_mul_f32_e32 v0, v5, v5
	v_mul_f32_e32 v1, v7, v7
	v_fmac_f32_e32 v0, v4, v4
	v_fmac_f32_e32 v1, v6, v6
	v_add_f32_e32 v0, v0, v1
	v_mul_f32_e32 v1, v9, v9
	v_fmac_f32_e32 v1, v8, v8
	v_add_f32_e32 v0, v1, v0
	v_mul_f32_e32 v1, v11, v11
	v_fmac_f32_e32 v1, v10, v10
	v_add_f32_e32 v0, v1, v0
	v_add_f32_e32 v0, v12, v0
	ds_bpermute_b32 v1, v112, v0
	s_waitcnt lgkmcnt(0)
	v_add_f32_e32 v0, v0, v1
	ds_bpermute_b32 v1, v113, v0
	s_and_saveexec_b64 s[24:25], s[38:39]
	s_cbranch_execz .LBB0_1078
	v_lshlrev_b32_e32 v2, 6, v16
	s_waitcnt lgkmcnt(0)
	v_add_f32_e32 v0, v0, v1
	global_store_dword v2, v0, s[54:55]

;     __device__ __forceinline__ void operator()(const f32x4 (&acc)[2][2][4][2], const Unit& u, int wr, int wc, int fr, int fq) const {
;     ...
;                 const int row = row0 + ai * HALF + m * 16;
;                 const f32x4* sp = (const f32x4*)(ss + (size_t)row * 16);
;                 const f32x4 a0 = sp[0], a1 = sp[1], a2 = sp[2], a3 = sp[3];
;                 const float tot = ((a0.x + a0.y) + (a0.z + a0.w)) + ((a1.x + a1.y) + (a1.z + a1.w)) + ((a2.x + a2.y) + (a2.z + a2.w)) + ((a3.x + a3.y) + (a3.z + a3.w));
;                 const float rs = rsqrtf(tot * (1.0f / 1024.0f) + 1e-6f);
;                 bf16_t* rowp = O + (size_t)row * ldc + col0;
.LBB0_1155:
	v_lshl_add_u32 v152, s88, 8, v154
	v_ashrrev_i32_e32 v153, 31, v152
	v_lshlrev_b64 v[176:177], 6, v[152:153]
	v_and_or_b32 v176, v204, 48, v176
	v_lshl_add_u64 v[176:177], s[90:91], 0, v[176:177]
	v_mov_b32_e32 v178, 0x2000
	v_mov_b32_e32 v179, 0
	v_lshl_add_u64 v[178:179], v[176:177], 0, v[178:179]
	global_load_dwordx4 v[180:183], v[176:177], off
	global_load_dwordx4 v[184:187], v[176:177], off offset:1024
	global_load_dwordx4 v[188:191], v[176:177], off offset:2048
	global_load_dwordx4 v[192:195], v[176:177], off offset:3072
	global_load_dwordx4 v[196:199], v[178:179], off
	global_load_dwordx4 v[208:211], v[178:179], off offset:1024
	global_load_dwordx4 v[212:215], v[178:179], off offset:2048
	global_load_dwordx4 v[216:219], v[178:179], off offset:3072
	v_lshl_or_b32 v150, s30, 8, v156
	v_ashrrev_i32_e32 v151, 31, v150
	v_lshlrev_b64 v[150:151], 1, v[150:151]
	s_mov_b64 s[24:25], -1
	v_lshlrev_b64 v[160:161], 13, v[152:153]
	v_lshl_add_u64 v[160:161], s[78:79], 0, v[160:161]
	v_lshl_add_u64 v[160:161], v[160:161], 0, v[150:151]
	s_waitcnt vmcnt(0)
	v_add_f32_e32 v180, v180, v181
	v_add_f32_e32 v182, v182, v183
	v_add_f32_e32 v184, v184, v185
	v_add_f32_e32 v186, v186, v187
	v_add_f32_e32 v188, v188, v189
	v_add_f32_e32 v190, v190, v191
	v_add_f32_e32 v192, v192, v193
	v_add_f32_e32 v194, v194, v195
	v_add_f32_e32 v196, v196, v197
	v_add_f32_e32 v198, v198, v199
	v_add_f32_e32 v208, v208, v209
	v_add_f32_e32 v210, v210, v211
	v_add_f32_e32 v212, v212, v213
	v_add_f32_e32 v214, v214, v215
	v_add_f32_e32 v216, v216, v217
	v_add_f32_e32 v218, v218, v219
	v_add_f32_e32 v180, v180, v182
	v_add_f32_e32 v184, v184, v186
	v_add_f32_e32 v188, v188, v190
	v_add_f32_e32 v192, v192, v194
	v_add_f32_e32 v196, v196, v198
	v_add_f32_e32 v208, v208, v210
	v_add_f32_e32 v212, v212, v214
	v_add_f32_e32 v216, v216, v218
	v_mov_b32_e32 v181, v180
	v_mov_b32_e32 v185, v184
	v_mov_b32_e32 v189, v188
	v_mov_b32_e32 v193, v192
	v_mov_b32_e32 v197, v196
	v_mov_b32_e32 v209, v208
	v_mov_b32_e32 v213, v212
	v_mov_b32_e32 v217, v216
	s_nop 1
	v_permlane16_swap_b32_e32 v180, v181
	v_permlane16_swap_b32_e32 v184, v185
	v_permlane16_swap_b32_e32 v188, v189
	v_permlane16_swap_b32_e32 v192, v193
	v_permlane16_swap_b32_e32 v196, v197
	v_permlane16_swap_b32_e32 v208, v209
	v_permlane16_swap_b32_e32 v212, v213
	v_permlane16_swap_b32_e32 v216, v217
	v_add_f32_e32 v180, v180, v181
	v_add_f32_e32 v184, v184, v185
	v_add_f32_e32 v188, v188, v189
	v_add_f32_e32 v192, v192, v193
	v_add_f32_e32 v196, v196, v197
	v_add_f32_e32 v208, v208, v209
	v_add_f32_e32 v212, v212, v213
	v_add_f32_e32 v216, v216, v217
	v_mov_b32_e32 v181, v180
	v_mov_b32_e32 v185, v184
	v_mov_b32_e32 v189, v188
	v_mov_b32_e32 v193, v192
	v_mov_b32_e32 v197, v196
	v_mov_b32_e32 v209, v208
	v_mov_b32_e32 v213, v212
	v_mov_b32_e32 v217, v216
	s_nop 1
	v_permlane32_swap_b32_e32 v180, v181
	v_permlane32_swap_b32_e32 v184, v185
	v_permlane32_swap_b32_e32 v188, v189
	v_permlane32_swap_b32_e32 v192, v193
	v_permlane32_swap_b32_e32 v196, v197
	v_permlane32_swap_b32_e32 v208, v209
	v_permlane32_swap_b32_e32 v212, v213
	v_permlane32_swap_b32_e32 v216, v217
	v_add_f32_e32 v180, v180, v181
	v_add_f32_e32 v184, v184, v185
	v_add_f32_e32 v188, v188, v189
	v_add_f32_e32 v192, v192, v193
	v_add_f32_e32 v196, v196, v197
	v_add_f32_e32 v208, v208, v209
	v_add_f32_e32 v212, v212, v213
	v_add_f32_e32 v216, v216, v217
	v_fmamk_f32 v180, v180, 0x3a800000, v137
	v_cmp_gt_f32_e32 vcc, s4, v180
	v_mul_f32_e32 v181, 0x4b800000, v180
	s_nop 0
	v_cndmask_b32_e32 v180, v180, v181, vcc
	v_rsq_f32_e32 v180, v180
	s_nop 0
	v_mul_f32_e32 v181, 0x45800000, v180
	v_cndmask_b32_e32 v180, v180, v181, vcc
	v_fmamk_f32 v184, v184, 0x3a800000, v137
	v_cmp_gt_f32_e32 vcc, s4, v184
	v_mul_f32_e32 v185, 0x4b800000, v184
	s_nop 0
	v_cndmask_b32_e32 v184, v184, v185, vcc
	v_rsq_f32_e32 v184, v184
	s_nop 0
	v_mul_f32_e32 v185, 0x45800000, v184
	v_cndmask_b32_e32 v184, v184, v185, vcc
	v_fmamk_f32 v188, v188, 0x3a800000, v137
	v_cmp_gt_f32_e32 vcc, s4, v188
	v_mul_f32_e32 v189, 0x4b800000, v188
	s_nop 0
	v_cndmask_b32_e32 v188, v188, v189, vcc
	v_rsq_f32_e32 v188, v188
	s_nop 0
	v_mul_f32_e32 v189, 0x45800000, v188
	v_cndmask_b32_e32 v188, v188, v189, vcc
	v_fmamk_f32 v192, v192, 0x3a800000, v137
	v_cmp_gt_f32_e32 vcc, s4, v192
	v_mul_f32_e32 v193, 0x4b800000, v192
	s_nop 0
	v_cndmask_b32_e32 v192, v192, v193, vcc
	v_rsq_f32_e32 v192, v192
	s_nop 0
	v_mul_f32_e32 v193, 0x45800000, v192
	v_cndmask_b32_e32 v192, v192, v193, vcc
	v_fmamk_f32 v196, v196, 0x3a800000, v137
	v_cmp_gt_f32_e32 vcc, s4, v196
	v_mul_f32_e32 v197, 0x4b800000, v196
	s_nop 0
	v_cndmask_b32_e32 v196, v196, v197, vcc
	v_rsq_f32_e32 v196, v196
	s_nop 0
	v_mul_f32_e32 v197, 0x45800000, v196
	v_cndmask_b32_e32 v196, v196, v197, vcc
	v_fmamk_f32 v208, v208, 0x3a800000, v137
	v_cmp_gt_f32_e32 vcc, s4, v208
	v_mul_f32_e32 v209, 0x4b800000, v208
	s_nop 0
	v_cndmask_b32_e32 v208, v208, v209, vcc
	v_rsq_f32_e32 v208, v208
	s_nop 0
	v_mul_f32_e32 v209, 0x45800000, v208
	v_cndmask_b32_e32 v208, v208, v209, vcc
	v_fmamk_f32 v212, v212, 0x3a800000, v137
	v_cmp_gt_f32_e32 vcc, s4, v212
	v_mul_f32_e32 v213, 0x4b800000, v212
	s_nop 0
	v_cndmask_b32_e32 v212, v212, v213, vcc
	v_rsq_f32_e32 v212, v212
	s_nop 0
	v_mul_f32_e32 v213, 0x45800000, v212
	v_cndmask_b32_e32 v212, v212, v213, vcc
	v_fmamk_f32 v216, v216, 0x3a800000, v137
	v_cmp_gt_f32_e32 vcc, s4, v216
	v_mul_f32_e32 v217, 0x4b800000, v216
	s_nop 0
	v_cndmask_b32_e32 v216, v216, v217, vcc
	v_rsq_f32_e32 v216, v216
	s_nop 0
	v_mul_f32_e32 v217, 0x45800000, v216
	v_cndmask_b32_e32 v216, v216, v217, vcc
	v_mov_b32_e32 v158, v180
; __device__ __forceinline__ unsigned cvt_pk_bf16(float lo, float hi) { unsigned r; asm volatile("v_cvt_pk_bf16_f32 %0, %1, %2" : "=v"(r) : "v"(lo), "v"(hi)); return r; }
;     __device__ __forceinline__ void operator()(const f32x4 (&acc)[2][2][4][2], const Unit& u, int wr, int wc, int fr, int fq) const {
;     ...
;                 const int row = row0 + ai * HALF + m * 16;
;                 const f32x4* sp = (const f32x4*)(ss + (size_t)row * 16);
;                 const f32x4 a0 = sp[0], a1 = sp[1], a2 = sp[2], a3 = sp[3];
;                 const float tot = ((a0.x + a0.y) + (a0.z + a0.w)) + ((a1.x + a1.y) + (a1.z + a1.w)) + ((a2.x + a2.y) + (a2.z + a2.w)) + ((a3.x + a3.y) + (a3.z + a3.w));
;                 const float rs = rsqrtf(tot * (1.0f / 1024.0f) + 1e-6f);
;                 bf16_t* rowp = O + (size_t)row * ldc + col0;
; #pragma unroll
;                 for (int bj = 0; bj < 2; ++bj) {
;                     f32x4 v0 = acc[ai][bj][m][0] * rs, v1 = acc[ai][bj][m][1] * rs;
;                     if (ACT == 1) {
; #pragma unroll
;                         for (int e = 0; e < 4; ++e) { float a = fmaxf(v0[e], 0.f); v0[e] = a * a; float b = fmaxf(v1[e], 0.f); v1[e] = b * b; }
;                     }
;                     u32x4 w; w.x = cvt_pk_bf16(v0[0], v0[1]); w.y = cvt_pk_bf16(v0[2], v0[3]); w.z = cvt_pk_bf16(v1[0], v1[1]); w.w = cvt_pk_bf16(v1[2], v1[3]);
;                     *(u32x4*)(rowp + bj * HALF) = w;
	v_pk_mul_f32 v[120:121], v[120:121], v[158:159] op_sel_hi:[1,0]
	v_pk_mul_f32 v[124:125], v[124:125], v[158:159] op_sel_hi:[1,0]
	v_pk_mul_f32 v[122:123], v[122:123], v[158:159] op_sel_hi:[1,0]
	v_max_f32_e32 v120, 0, v120
	v_pk_mul_f32 v[126:127], v[126:127], v[158:159] op_sel_hi:[1,0]
	v_mul_f32_e32 v153, v120, v120
	v_max_f32_e32 v120, 0, v125
	v_max_f32_e32 v121, 0, v121
	v_max_f32_e32 v122, 0, v122
	v_max_f32_e32 v124, 0, v124
	v_mul_f32_e32 v120, v120, v120
	v_mul_f32_e32 v125, v121, v121
	v_max_f32_e32 v121, 0, v126
	v_mul_f32_e32 v126, v122, v122
	v_max_f32_e32 v122, 0, v127
	v_max_f32_e32 v123, 0, v123
	v_pk_mul_f32 v[112:113], v[112:113], v[158:159] op_sel_hi:[1,0]
	v_mul_f32_e32 v124, v124, v124
	v_mul_f32_e32 v121, v121, v121
	v_mul_f32_e32 v122, v122, v122
	v_mul_f32_e32 v123, v123, v123
	v_cvt_pk_bf16_f32 v120, v124, v120
	v_pk_mul_f32 v[116:117], v[116:117], v[158:159] op_sel_hi:[1,0]
	v_pk_mul_f32 v[114:115], v[114:115], v[158:159] op_sel_hi:[1,0]
	v_max_f32_e32 v112, 0, v112
	v_cvt_pk_bf16_f32 v121, v121, v122
	v_cvt_pk_bf16_f32 v122, v153, v125
	v_cvt_pk_bf16_f32 v123, v126, v123
	global_store_dwordx4 v[160:161], v[120:123], off
	v_pk_mul_f32 v[118:119], v[118:119], v[158:159] op_sel_hi:[1,0]
	v_max_f32_e32 v113, 0, v113
	v_mul_f32_e32 v120, v112, v112
	v_max_f32_e32 v112, 0, v117
	v_max_f32_e32 v114, 0, v114
	v_max_f32_e32 v116, 0, v116
	v_mul_f32_e32 v112, v112, v112
	v_mul_f32_e32 v117, v113, v113
	v_max_f32_e32 v113, 0, v118
	v_mul_f32_e32 v118, v114, v114
	v_max_f32_e32 v114, 0, v119
	v_max_f32_e32 v115, 0, v115
	v_mul_f32_e32 v116, v116, v116
	v_mul_f32_e32 v113, v113, v113
	v_mul_f32_e32 v114, v114, v114
	v_mul_f32_e32 v115, v115, v115
	v_cvt_pk_bf16_f32 v112, v116, v112
	v_cvt_pk_bf16_f32 v113, v113, v114
	v_cvt_pk_bf16_f32 v114, v120, v117
	v_cvt_pk_bf16_f32 v115, v118, v115
	global_store_dwordx4 v[160:161], v[112:115], off offset:256
	s_nop 1
	v_or_b32_e32 v112, 16, v152
	v_ashrrev_i32_e32 v113, 31, v112
	v_lshlrev_b64 v[112:113], 13, v[112:113]
	v_lshl_add_u64 v[112:113], s[78:79], 0, v[112:113]
	v_lshl_add_u64 v[112:113], v[112:113], 0, v[150:151]
	v_mov_b32_e32 v114, v184
	v_pk_mul_f32 v[104:105], v[104:105], v[114:115] op_sel_hi:[1,0]
	v_pk_mul_f32 v[108:109], v[108:109], v[114:115] op_sel_hi:[1,0]
	v_pk_mul_f32 v[106:107], v[106:107], v[114:115] op_sel_hi:[1,0]
	v_max_f32_e32 v104, 0, v104
	v_pk_mul_f32 v[110:111], v[110:111], v[114:115] op_sel_hi:[1,0]
	v_mul_f32_e32 v115, v104, v104
	v_max_f32_e32 v104, 0, v109
	v_max_f32_e32 v105, 0, v105
	v_max_f32_e32 v106, 0, v106
	v_max_f32_e32 v108, 0, v108
	v_mul_f32_e32 v104, v104, v104
	v_mul_f32_e32 v109, v105, v105
	v_max_f32_e32 v105, 0, v110
	v_mul_f32_e32 v110, v106, v106
	v_max_f32_e32 v106, 0, v111
	v_max_f32_e32 v107, 0, v107
	v_pk_mul_f32 v[96:97], v[96:97], v[114:115] op_sel_hi:[1,0]
	v_mul_f32_e32 v108, v108, v108
	v_mul_f32_e32 v105, v105, v105
	v_mul_f32_e32 v106, v106, v106
	v_mul_f32_e32 v107, v107, v107
	v_cvt_pk_bf16_f32 v104, v108, v104
	v_pk_mul_f32 v[100:101], v[100:101], v[114:115] op_sel_hi:[1,0]
	v_pk_mul_f32 v[98:99], v[98:99], v[114:115] op_sel_hi:[1,0]
	v_max_f32_e32 v96, 0, v96
	v_cvt_pk_bf16_f32 v105, v105, v106
	v_cvt_pk_bf16_f32 v106, v115, v109
	v_cvt_pk_bf16_f32 v107, v110, v107
	global_store_dwordx4 v[112:113], v[104:107], off
	v_pk_mul_f32 v[102:103], v[102:103], v[114:115] op_sel_hi:[1,0]
	v_max_f32_e32 v97, 0, v97
	v_mul_f32_e32 v104, v96, v96
	v_max_f32_e32 v96, 0, v101
	v_max_f32_e32 v98, 0, v98
	v_max_f32_e32 v100, 0, v100
	v_mul_f32_e32 v96, v96, v96
	v_mul_f32_e32 v101, v97, v97
	v_max_f32_e32 v97, 0, v102
	v_mul_f32_e32 v102, v98, v98
	v_max_f32_e32 v98, 0, v103
	v_max_f32_e32 v99, 0, v99
	v_mul_f32_e32 v100, v100, v100
	v_mul_f32_e32 v97, v97, v97
	v_mul_f32_e32 v98, v98, v98
	v_mul_f32_e32 v99, v99, v99
	v_cvt_pk_bf16_f32 v96, v100, v96
	v_cvt_pk_bf16_f32 v97, v97, v98
	v_cvt_pk_bf16_f32 v98, v104, v101
	v_cvt_pk_bf16_f32 v99, v102, v99
	global_store_dwordx4 v[112:113], v[96:99], off offset:256
	s_nop 1
	v_or_b32_e32 v96, 32, v152
	v_ashrrev_i32_e32 v97, 31, v96
	v_lshlrev_b64 v[96:97], 13, v[96:97]
	v_lshl_add_u64 v[96:97], s[78:79], 0, v[96:97]
	v_lshl_add_u64 v[96:97], v[96:97], 0, v[150:151]
	v_mov_b32_e32 v98, v188
	v_pk_mul_f32 v[88:89], v[88:89], v[98:99] op_sel_hi:[1,0]
	v_pk_mul_f32 v[92:93], v[92:93], v[98:99] op_sel_hi:[1,0]
	v_pk_mul_f32 v[90:91], v[90:91], v[98:99] op_sel_hi:[1,0]
	v_max_f32_e32 v88, 0, v88
	v_pk_mul_f32 v[94:95], v[94:95], v[98:99] op_sel_hi:[1,0]
	v_mul_f32_e32 v99, v88, v88
	v_max_f32_e32 v88, 0, v93
	v_max_f32_e32 v89, 0, v89
	v_max_f32_e32 v90, 0, v90
	v_max_f32_e32 v92, 0, v92
	v_mul_f32_e32 v88, v88, v88
	v_mul_f32_e32 v93, v89, v89
	v_max_f32_e32 v89, 0, v94
	v_mul_f32_e32 v94, v90, v90
	v_max_f32_e32 v90, 0, v95
	v_max_f32_e32 v91, 0, v91
	v_pk_mul_f32 v[80:81], v[80:81], v[98:99] op_sel_hi:[1,0]
	v_mul_f32_e32 v92, v92, v92
	v_mul_f32_e32 v89, v89, v89
	v_mul_f32_e32 v90, v90, v90
	v_mul_f32_e32 v91, v91, v91
	v_cvt_pk_bf16_f32 v88, v92, v88
	v_pk_mul_f32 v[84:85], v[84:85], v[98:99] op_sel_hi:[1,0]
	v_pk_mul_f32 v[82:83], v[82:83], v[98:99] op_sel_hi:[1,0]
	v_max_f32_e32 v80, 0, v80
	v_cvt_pk_bf16_f32 v89, v89, v90
	v_cvt_pk_bf16_f32 v90, v99, v93
	v_cvt_pk_bf16_f32 v91, v94, v91
	global_store_dwordx4 v[96:97], v[88:91], off
	v_pk_mul_f32 v[86:87], v[86:87], v[98:99] op_sel_hi:[1,0]
	v_max_f32_e32 v81, 0, v81
	v_mul_f32_e32 v88, v80, v80
	v_max_f32_e32 v80, 0, v85
	v_max_f32_e32 v82, 0, v82
	v_max_f32_e32 v84, 0, v84
	v_mul_f32_e32 v80, v80, v80
	v_mul_f32_e32 v85, v81, v81
	v_max_f32_e32 v81, 0, v86
	v_mul_f32_e32 v86, v82, v82
	v_max_f32_e32 v82, 0, v87
	v_max_f32_e32 v83, 0, v83
; __device__ __forceinline__ unsigned cvt_pk_bf16(float lo, float hi) { unsigned r; asm volatile("v_cvt_pk_bf16_f32 %0, %1, %2" : "=v"(r) : "v"(lo), "v"(hi)); return r; }
;     __device__ __forceinline__ void operator()(const f32x4 (&acc)[2][2][4][2], const Unit& u, int wr, int wc, int fr, int fq) const {
;     ...
;                 const int row = row0 + ai * HALF + m * 16;
;                 const f32x4* sp = (const f32x4*)(ss + (size_t)row * 16);
;                 const f32x4 a0 = sp[0], a1 = sp[1], a2 = sp[2], a3 = sp[3];
;                 const float tot = ((a0.x + a0.y) + (a0.z + a0.w)) + ((a1.x + a1.y) + (a1.z + a1.w)) + ((a2.x + a2.y) + (a2.z + a2.w)) + ((a3.x + a3.y) + (a3.z + a3.w));
;                 const float rs = rsqrtf(tot * (1.0f / 1024.0f) + 1e-6f);
;                 bf16_t* rowp = O + (size_t)row * ldc + col0;
; #pragma unroll
;                 for (int bj = 0; bj < 2; ++bj) {
;                     f32x4 v0 = acc[ai][bj][m][0] * rs, v1 = acc[ai][bj][m][1] * rs;
;                     if (ACT == 1) {
; #pragma unroll
;                         for (int e = 0; e < 4; ++e) { float a = fmaxf(v0[e], 0.f); v0[e] = a * a; float b = fmaxf(v1[e], 0.f); v1[e] = b * b; }
;                     }
;                     u32x4 w; w.x = cvt_pk_bf16(v0[0], v0[1]); w.y = cvt_pk_bf16(v0[2], v0[3]); w.z = cvt_pk_bf16(v1[0], v1[1]); w.w = cvt_pk_bf16(v1[2], v1[3]);
;                     *(u32x4*)(rowp + bj * HALF) = w;
	v_mul_f32_e32 v84, v84, v84
	v_mul_f32_e32 v81, v81, v81
	v_mul_f32_e32 v82, v82, v82
	v_mul_f32_e32 v83, v83, v83
	v_cvt_pk_bf16_f32 v80, v84, v80
	v_cvt_pk_bf16_f32 v81, v81, v82
	v_cvt_pk_bf16_f32 v82, v88, v85
	v_cvt_pk_bf16_f32 v83, v86, v83
	global_store_dwordx4 v[96:97], v[80:83], off offset:256
	s_nop 1
	v_or_b32_e32 v80, 48, v152
	v_ashrrev_i32_e32 v81, 31, v80
	v_lshlrev_b64 v[80:81], 13, v[80:81]
	v_lshl_add_u64 v[80:81], s[78:79], 0, v[80:81]
	v_lshl_add_u64 v[80:81], v[80:81], 0, v[150:151]
	v_mov_b32_e32 v82, v192
	v_pk_mul_f32 v[72:73], v[72:73], v[82:83] op_sel_hi:[1,0]
	v_pk_mul_f32 v[76:77], v[76:77], v[82:83] op_sel_hi:[1,0]
	v_pk_mul_f32 v[74:75], v[74:75], v[82:83] op_sel_hi:[1,0]
	v_max_f32_e32 v72, 0, v72
	v_pk_mul_f32 v[78:79], v[78:79], v[82:83] op_sel_hi:[1,0]
	v_mul_f32_e32 v83, v72, v72
	v_max_f32_e32 v72, 0, v77
	v_max_f32_e32 v73, 0, v73
	v_max_f32_e32 v74, 0, v74
	v_max_f32_e32 v76, 0, v76
	v_mul_f32_e32 v72, v72, v72
	v_mul_f32_e32 v77, v73, v73
	v_max_f32_e32 v73, 0, v78
	v_mul_f32_e32 v78, v74, v74
	v_max_f32_e32 v74, 0, v79
	v_max_f32_e32 v75, 0, v75
	v_pk_mul_f32 v[64:65], v[64:65], v[82:83] op_sel_hi:[1,0]
	v_mul_f32_e32 v76, v76, v76
	v_mul_f32_e32 v73, v73, v73
	v_mul_f32_e32 v74, v74, v74
	v_mul_f32_e32 v75, v75, v75
	v_cvt_pk_bf16_f32 v72, v76, v72
	v_pk_mul_f32 v[68:69], v[68:69], v[82:83] op_sel_hi:[1,0]
	v_pk_mul_f32 v[66:67], v[66:67], v[82:83] op_sel_hi:[1,0]
	v_max_f32_e32 v64, 0, v64
	v_cvt_pk_bf16_f32 v73, v73, v74
	v_cvt_pk_bf16_f32 v74, v83, v77
	v_cvt_pk_bf16_f32 v75, v78, v75
	global_store_dwordx4 v[80:81], v[72:75], off
	v_pk_mul_f32 v[70:71], v[70:71], v[82:83] op_sel_hi:[1,0]
	v_max_f32_e32 v65, 0, v65
	v_mul_f32_e32 v72, v64, v64
	v_max_f32_e32 v64, 0, v69
	v_max_f32_e32 v66, 0, v66
	v_max_f32_e32 v68, 0, v68
	v_mul_f32_e32 v64, v64, v64
	v_mul_f32_e32 v69, v65, v65
	v_max_f32_e32 v65, 0, v70
	v_mul_f32_e32 v70, v66, v66
	v_max_f32_e32 v66, 0, v71
	v_max_f32_e32 v67, 0, v67
	v_mul_f32_e32 v68, v68, v68
	v_mul_f32_e32 v65, v65, v65
	v_mul_f32_e32 v66, v66, v66
	v_mul_f32_e32 v67, v67, v67
	v_cvt_pk_bf16_f32 v64, v68, v64
	v_cvt_pk_bf16_f32 v65, v65, v66
	v_cvt_pk_bf16_f32 v66, v72, v69
	v_cvt_pk_bf16_f32 v67, v70, v67
	global_store_dwordx4 v[80:81], v[64:67], off offset:256
	s_nop 1
	v_add_u32_e32 v64, 0x80, v152
	v_ashrrev_i32_e32 v65, 31, v64
	v_lshlrev_b64 v[64:65], 13, v[64:65]
	v_lshl_add_u64 v[64:65], s[78:79], 0, v[64:65]
	v_lshl_add_u64 v[64:65], v[64:65], 0, v[150:151]
	v_mov_b32_e32 v66, v196
	v_pk_mul_f32 v[56:57], v[56:57], v[66:67] op_sel_hi:[1,0]
	v_pk_mul_f32 v[60:61], v[60:61], v[66:67] op_sel_hi:[1,0]
	v_pk_mul_f32 v[58:59], v[58:59], v[66:67] op_sel_hi:[1,0]
	v_max_f32_e32 v56, 0, v56
	v_pk_mul_f32 v[62:63], v[62:63], v[66:67] op_sel_hi:[1,0]
	v_mul_f32_e32 v67, v56, v56
	v_max_f32_e32 v56, 0, v61
	v_max_f32_e32 v57, 0, v57
	v_max_f32_e32 v58, 0, v58
	v_max_f32_e32 v60, 0, v60
	v_mul_f32_e32 v56, v56, v56
	v_mul_f32_e32 v61, v57, v57
	v_max_f32_e32 v57, 0, v62
	v_mul_f32_e32 v62, v58, v58
	v_max_f32_e32 v58, 0, v63
	v_max_f32_e32 v59, 0, v59
	v_pk_mul_f32 v[48:49], v[48:49], v[66:67] op_sel_hi:[1,0]
	v_mul_f32_e32 v60, v60, v60
	v_mul_f32_e32 v57, v57, v57
	v_mul_f32_e32 v58, v58, v58
	v_mul_f32_e32 v59, v59, v59
	v_cvt_pk_bf16_f32 v56, v60, v56
	v_pk_mul_f32 v[52:53], v[52:53], v[66:67] op_sel_hi:[1,0]
	v_pk_mul_f32 v[50:51], v[50:51], v[66:67] op_sel_hi:[1,0]
	v_max_f32_e32 v48, 0, v48
	v_cvt_pk_bf16_f32 v57, v57, v58
	v_cvt_pk_bf16_f32 v58, v67, v61
	v_cvt_pk_bf16_f32 v59, v62, v59
	global_store_dwordx4 v[64:65], v[56:59], off
	v_pk_mul_f32 v[54:55], v[54:55], v[66:67] op_sel_hi:[1,0]
	v_max_f32_e32 v49, 0, v49
	v_mul_f32_e32 v56, v48, v48
	v_max_f32_e32 v48, 0, v53
	v_max_f32_e32 v50, 0, v50
	v_max_f32_e32 v52, 0, v52
	v_mul_f32_e32 v48, v48, v48
	v_mul_f32_e32 v53, v49, v49
	v_max_f32_e32 v49, 0, v54
	v_mul_f32_e32 v54, v50, v50
	v_max_f32_e32 v50, 0, v55
	v_max_f32_e32 v51, 0, v51
	v_mul_f32_e32 v52, v52, v52
	v_mul_f32_e32 v49, v49, v49
	v_mul_f32_e32 v50, v50, v50
	v_mul_f32_e32 v51, v51, v51
	v_cvt_pk_bf16_f32 v48, v52, v48
	v_cvt_pk_bf16_f32 v49, v49, v50
	v_cvt_pk_bf16_f32 v50, v56, v53
	v_cvt_pk_bf16_f32 v51, v54, v51
	global_store_dwordx4 v[64:65], v[48:51], off offset:256
	s_nop 1
	v_add_u32_e32 v48, 0x90, v152
	v_ashrrev_i32_e32 v49, 31, v48
	v_lshlrev_b64 v[48:49], 13, v[48:49]
	v_lshl_add_u64 v[48:49], s[78:79], 0, v[48:49]
	v_lshl_add_u64 v[48:49], v[48:49], 0, v[150:151]
	v_mov_b32_e32 v50, v208
	v_pk_mul_f32 v[40:41], v[40:41], v[50:51] op_sel_hi:[1,0]
	v_pk_mul_f32 v[44:45], v[44:45], v[50:51] op_sel_hi:[1,0]
	v_pk_mul_f32 v[42:43], v[42:43], v[50:51] op_sel_hi:[1,0]
	v_max_f32_e32 v40, 0, v40
	v_pk_mul_f32 v[46:47], v[46:47], v[50:51] op_sel_hi:[1,0]
	v_mul_f32_e32 v51, v40, v40
	v_max_f32_e32 v40, 0, v45
	v_max_f32_e32 v41, 0, v41
	v_max_f32_e32 v42, 0, v42
	v_max_f32_e32 v44, 0, v44
	v_mul_f32_e32 v40, v40, v40
	v_mul_f32_e32 v45, v41, v41
	v_max_f32_e32 v41, 0, v46
	v_mul_f32_e32 v46, v42, v42
	v_max_f32_e32 v42, 0, v47
	v_max_f32_e32 v43, 0, v43
	v_pk_mul_f32 v[32:33], v[32:33], v[50:51] op_sel_hi:[1,0]
; __device__ __forceinline__ unsigned cvt_pk_bf16(float lo, float hi) { unsigned r; asm volatile("v_cvt_pk_bf16_f32 %0, %1, %2" : "=v"(r) : "v"(lo), "v"(hi)); return r; }
;     __device__ __forceinline__ void operator()(const f32x4 (&acc)[2][2][4][2], const Unit& u, int wr, int wc, int fr, int fq) const {
;     ...
;                 const int row = row0 + ai * HALF + m * 16;
;                 const f32x4* sp = (const f32x4*)(ss + (size_t)row * 16);
;                 const f32x4 a0 = sp[0], a1 = sp[1], a2 = sp[2], a3 = sp[3];
;                 const float tot = ((a0.x + a0.y) + (a0.z + a0.w)) + ((a1.x + a1.y) + (a1.z + a1.w)) + ((a2.x + a2.y) + (a2.z + a2.w)) + ((a3.x + a3.y) + (a3.z + a3.w));
;                 const float rs = rsqrtf(tot * (1.0f / 1024.0f) + 1e-6f);
;                 bf16_t* rowp = O + (size_t)row * ldc + col0;
; #pragma unroll
;                 for (int bj = 0; bj < 2; ++bj) {
;                     f32x4 v0 = acc[ai][bj][m][0] * rs, v1 = acc[ai][bj][m][1] * rs;
;                     if (ACT == 1) {
; #pragma unroll
;                         for (int e = 0; e < 4; ++e) { float a = fmaxf(v0[e], 0.f); v0[e] = a * a; float b = fmaxf(v1[e], 0.f); v1[e] = b * b; }
;                     }
;                     u32x4 w; w.x = cvt_pk_bf16(v0[0], v0[1]); w.y = cvt_pk_bf16(v0[2], v0[3]); w.z = cvt_pk_bf16(v1[0], v1[1]); w.w = cvt_pk_bf16(v1[2], v1[3]);
;                     *(u32x4*)(rowp + bj * HALF) = w;
	v_mul_f32_e32 v44, v44, v44
	v_mul_f32_e32 v41, v41, v41
	v_mul_f32_e32 v42, v42, v42
	v_mul_f32_e32 v43, v43, v43
	v_cvt_pk_bf16_f32 v40, v44, v40
	v_pk_mul_f32 v[36:37], v[36:37], v[50:51] op_sel_hi:[1,0]
	v_pk_mul_f32 v[34:35], v[34:35], v[50:51] op_sel_hi:[1,0]
	v_max_f32_e32 v32, 0, v32
	v_cvt_pk_bf16_f32 v41, v41, v42
	v_cvt_pk_bf16_f32 v42, v51, v45
	v_cvt_pk_bf16_f32 v43, v46, v43
	global_store_dwordx4 v[48:49], v[40:43], off
	v_pk_mul_f32 v[38:39], v[38:39], v[50:51] op_sel_hi:[1,0]
	v_max_f32_e32 v33, 0, v33
	v_mul_f32_e32 v40, v32, v32
	v_max_f32_e32 v32, 0, v37
	v_max_f32_e32 v34, 0, v34
	v_max_f32_e32 v36, 0, v36
	v_mul_f32_e32 v32, v32, v32
	v_mul_f32_e32 v37, v33, v33
	v_max_f32_e32 v33, 0, v38
	v_mul_f32_e32 v38, v34, v34
	v_max_f32_e32 v34, 0, v39
	v_max_f32_e32 v35, 0, v35
	v_mul_f32_e32 v36, v36, v36
	v_mul_f32_e32 v33, v33, v33
	v_mul_f32_e32 v34, v34, v34
	v_mul_f32_e32 v35, v35, v35
	v_cvt_pk_bf16_f32 v32, v36, v32
	v_cvt_pk_bf16_f32 v33, v33, v34
	v_cvt_pk_bf16_f32 v34, v40, v37
	v_cvt_pk_bf16_f32 v35, v38, v35
	global_store_dwordx4 v[48:49], v[32:35], off offset:256
	s_nop 1
	v_add_u32_e32 v32, 0xa0, v152
	v_ashrrev_i32_e32 v33, 31, v32
	v_lshlrev_b64 v[32:33], 13, v[32:33]
	v_lshl_add_u64 v[32:33], s[78:79], 0, v[32:33]
	v_lshl_add_u64 v[32:33], v[32:33], 0, v[150:151]
	v_mov_b32_e32 v34, v212
	v_pk_mul_f32 v[24:25], v[24:25], v[34:35] op_sel_hi:[1,0]
	v_pk_mul_f32 v[28:29], v[28:29], v[34:35] op_sel_hi:[1,0]
	v_pk_mul_f32 v[26:27], v[26:27], v[34:35] op_sel_hi:[1,0]
	v_max_f32_e32 v24, 0, v24
	v_pk_mul_f32 v[30:31], v[30:31], v[34:35] op_sel_hi:[1,0]
	v_mul_f32_e32 v35, v24, v24
	v_max_f32_e32 v24, 0, v29
	v_max_f32_e32 v25, 0, v25
	v_max_f32_e32 v26, 0, v26
	v_max_f32_e32 v28, 0, v28
	v_mul_f32_e32 v24, v24, v24
	v_mul_f32_e32 v29, v25, v25
	v_max_f32_e32 v25, 0, v30
	v_mul_f32_e32 v30, v26, v26
	v_max_f32_e32 v26, 0, v31
	v_max_f32_e32 v27, 0, v27
	v_pk_mul_f32 v[16:17], v[16:17], v[34:35] op_sel_hi:[1,0]
	v_mul_f32_e32 v28, v28, v28
	v_mul_f32_e32 v25, v25, v25
	v_mul_f32_e32 v26, v26, v26
	v_mul_f32_e32 v27, v27, v27
	v_cvt_pk_bf16_f32 v24, v28, v24
	v_pk_mul_f32 v[20:21], v[20:21], v[34:35] op_sel_hi:[1,0]
	v_pk_mul_f32 v[18:19], v[18:19], v[34:35] op_sel_hi:[1,0]
	v_max_f32_e32 v16, 0, v16
	v_cvt_pk_bf16_f32 v25, v25, v26
	v_cvt_pk_bf16_f32 v26, v35, v29
	v_cvt_pk_bf16_f32 v27, v30, v27
	global_store_dwordx4 v[32:33], v[24:27], off
	v_pk_mul_f32 v[22:23], v[22:23], v[34:35] op_sel_hi:[1,0]
	v_max_f32_e32 v17, 0, v17
	v_mul_f32_e32 v24, v16, v16
	v_max_f32_e32 v16, 0, v21
	v_max_f32_e32 v18, 0, v18
	v_max_f32_e32 v20, 0, v20
	v_mul_f32_e32 v16, v16, v16
	v_mul_f32_e32 v21, v17, v17
	v_max_f32_e32 v17, 0, v22
	v_mul_f32_e32 v22, v18, v18
	v_max_f32_e32 v18, 0, v23
	v_max_f32_e32 v19, 0, v19
	v_mul_f32_e32 v20, v20, v20
	v_mul_f32_e32 v17, v17, v17
	v_mul_f32_e32 v18, v18, v18
	v_mul_f32_e32 v19, v19, v19
	v_cvt_pk_bf16_f32 v16, v20, v16
	v_cvt_pk_bf16_f32 v17, v17, v18
	v_cvt_pk_bf16_f32 v18, v24, v21
	v_cvt_pk_bf16_f32 v19, v22, v19
	global_store_dwordx4 v[32:33], v[16:19], off offset:256
	s_nop 1
	v_add_u32_e32 v16, 0xb0, v152
	v_ashrrev_i32_e32 v17, 31, v16
	v_lshlrev_b64 v[16:17], 13, v[16:17]
	v_lshl_add_u64 v[16:17], s[78:79], 0, v[16:17]
	v_lshl_add_u64 v[16:17], v[16:17], 0, v[150:151]
	v_mov_b32_e32 v18, v216
	v_pk_mul_f32 v[8:9], v[8:9], v[18:19] op_sel_hi:[1,0]
	v_pk_mul_f32 v[12:13], v[12:13], v[18:19] op_sel_hi:[1,0]
	v_pk_mul_f32 v[10:11], v[10:11], v[18:19] op_sel_hi:[1,0]
	v_max_f32_e32 v8, 0, v8
	v_pk_mul_f32 v[14:15], v[14:15], v[18:19] op_sel_hi:[1,0]
	v_mul_f32_e32 v19, v8, v8
	v_max_f32_e32 v8, 0, v13
	v_max_f32_e32 v9, 0, v9
	v_max_f32_e32 v10, 0, v10
	v_max_f32_e32 v12, 0, v12
	v_mul_f32_e32 v8, v8, v8
	v_mul_f32_e32 v13, v9, v9
	v_max_f32_e32 v9, 0, v14
	v_mul_f32_e32 v14, v10, v10
	v_max_f32_e32 v10, 0, v15
	v_max_f32_e32 v11, 0, v11
	v_pk_mul_f32 v[2:3], v[2:3], v[18:19] op_sel_hi:[1,0]
	v_pk_mul_f32 v[0:1], v[0:1], v[18:19] op_sel_hi:[1,0]
	v_mul_f32_e32 v12, v12, v12
	v_mul_f32_e32 v9, v9, v9
	v_mul_f32_e32 v10, v10, v10
	v_mul_f32_e32 v11, v11, v11
	v_cvt_pk_bf16_f32 v8, v12, v8
	v_pk_mul_f32 v[6:7], v[6:7], v[18:19] op_sel_hi:[1,0]
	v_pk_mul_f32 v[4:5], v[4:5], v[18:19] op_sel_hi:[1,0]
	v_max_f32_e32 v0, 0, v0
	v_max_f32_e32 v1, 0, v1
	v_max_f32_e32 v2, 0, v2
	v_cvt_pk_bf16_f32 v9, v9, v10
	v_cvt_pk_bf16_f32 v10, v19, v13
	v_cvt_pk_bf16_f32 v11, v14, v11
	global_store_dwordx4 v[16:17], v[8:11], off
	v_max_f32_e32 v3, 0, v3
	v_max_f32_e32 v4, 0, v4
	v_mul_f32_e32 v8, v0, v0
	v_max_f32_e32 v0, 0, v5
	v_mul_f32_e32 v5, v1, v1
	v_max_f32_e32 v1, 0, v6
	v_mul_f32_e32 v6, v2, v2
	v_max_f32_e32 v2, 0, v7
	v_mul_f32_e32 v0, v0, v0
	v_mul_f32_e32 v1, v1, v1
	v_mul_f32_e32 v2, v2, v2
	v_mul_f32_e32 v3, v3, v3
	s_andn2_b64 vcc, exec, s[38:39]
	v_mul_f32_e32 v4, v4, v4
	v_cvt_pk_bf16_f32 v0, v4, v0
	v_cvt_pk_bf16_f32 v1, v1, v2
	v_cvt_pk_bf16_f32 v2, v8, v5
	v_cvt_pk_bf16_f32 v3, v6, v3
	global_store_dwordx4 v[16:17], v[0:3], off offset:256
	s_cbranch_vccnz .LBB0_1144
	s_andn2_b64 vcc, exec, s[0:1]
	s_cbranch_vccnz .LBB0_1143
	s_barrier
	s_branch .LBB0_1143

; __device__ __forceinline__ unsigned cvt_pk_bf16(float lo, float hi) { unsigned r; asm volatile("v_cvt_pk_bf16_f32 %0, %1, %2" : "=v"(r) : "v"(lo), "v"(hi)); return r; }
;     __device__ __forceinline__ void operator()(const f32x4 (&acc)[2][2][4][2], const Unit& u, int wr, int wc, int fr, int fq) const {
;     ...
;                 const unsigned row = row0 + ai * HALF + m * 16;
;                 const unsigned hoff = (row * 1024u + col0) * 2u;
;                 float sq = 0.f;
; #pragma unroll
;                 for (int bj = 0; bj < 2; ++bj) {
;                     const u32x4 xw = *(const u32x4*)(xbp + hoff + bj * (HALF * 2));
;                     f32x4 v0, v1;
;                     v0[0] = __uint_as_float(xw.x << 16) + acc[ai][bj][m][0][0]; v0[1] = __uint_as_float(xw.x & 0xffff0000u) + acc[ai][bj][m][0][1];
;                     v0[2] = __uint_as_float(xw.y << 16) + acc[ai][bj][m][0][2]; v0[3] = __uint_as_float(xw.y & 0xffff0000u) + acc[ai][bj][m][0][3];
;                     v1[0] = __uint_as_float(xw.z << 16) + acc[ai][bj][m][1][0]; v1[1] = __uint_as_float(xw.z & 0xffff0000u) + acc[ai][bj][m][1][1];
;                     v1[2] = __uint_as_float(xw.w << 16) + acc[ai][bj][m][1][2]; v1[3] = __uint_as_float(xw.w & 0xffff0000u) + acc[ai][bj][m][1][3];
;                     if (xout) { *(f32x4*)(xo + 2u * hoff + bj * (HALF * 4)) = v0; *(f32x4*)(xo + 2u * hoff + bj * (HALF * 4) + 16) = v1; }
;                     u32x4 w; w.x = cvt_pk_bf16(v0[0], v0[1]); w.y = cvt_pk_bf16(v0[2], v0[3]); w.z = cvt_pk_bf16(v1[0], v1[1]); w.w = cvt_pk_bf16(v1[2], v1[3]);
;                     *(u32x4*)(xbp + hoff + bj * (HALF * 2)) = w;
;                     sq += (v0[0] * v0[0] + v0[1] * v0[1]) + (v0[2] * v0[2] + v0[3] * v0[3]) + (v1[0] * v1[0] + v1[1] * v1[1]) + (v1[2] * v1[2] + v1[3] * v1[3]);
;                 }
;                 sq += __shfl_xor(sq, 16); sq += __shfl_xor(sq, 32);
;                 if (fq == 0) *(float*)(ssp + row * 64u + ssoff) = sq;
.LBB0_1232:
	v_lshl_add_u32 v160, s53, 8, v156
	v_lshl_or_b32 v161, s52, 9, v158
	v_lshl_add_u32 v154, v160, 11, v161
	v_add_u32_e32 v240, 0x8000, v154
	v_add_u32_e32 v241, 0x10000, v154
	v_add_u32_e32 v242, 0x18000, v154
	v_add_u32_e32 v243, 0x40000, v154
	v_add_u32_e32 v244, 0x48000, v154
	v_add_u32_e32 v245, 0x50000, v154
	v_add_u32_e32 v246, 0x58000, v154
	global_load_dwordx4 v[172:175], v154, s[72:73]
	global_load_dwordx4 v[176:179], v154, s[72:73] offset:256
	global_load_dwordx4 v[180:183], v240, s[72:73]
	global_load_dwordx4 v[184:187], v240, s[72:73] offset:256
	global_load_dwordx4 v[188:191], v241, s[72:73]
	global_load_dwordx4 v[192:195], v241, s[72:73] offset:256
	global_load_dwordx4 v[196:199], v242, s[72:73]
	global_load_dwordx4 v[200:203], v242, s[72:73] offset:256
	global_load_dwordx4 v[208:211], v243, s[72:73]
	global_load_dwordx4 v[212:215], v243, s[72:73] offset:256
	global_load_dwordx4 v[216:219], v244, s[72:73]
	global_load_dwordx4 v[220:223], v244, s[72:73] offset:256
	global_load_dwordx4 v[224:227], v245, s[72:73]
	global_load_dwordx4 v[228:231], v245, s[72:73] offset:256
	global_load_dwordx4 v[232:235], v246, s[72:73]
	global_load_dwordx4 v[236:239], v246, s[72:73] offset:256
	v_lshlrev_b32_e32 v138, 1, v154
	v_lshl_add_u64 v[152:153], s[22:23], 0, v[138:139]
	v_cndmask_b32_e64 v138, 0, 1, s[60:61]
	v_readlane_b32 s96, v250, 25
	v_cmp_ne_u32_e64 s[40:41], 1, v138
	s_andn2_b64 vcc, exec, s[60:61]
	v_readlane_b32 s97, v250, 26
	s_waitcnt vmcnt(15)
	s_nop 1
	v_mov_b32_e32 v162, v172
	v_mov_b32_e32 v163, v173
	v_mov_b32_e32 v164, v174
	v_mov_b32_e32 v165, v175
	v_lshlrev_b32_e32 v166, 16, v162
	v_and_b32_e32 v167, 0xffff0000, v162
	v_lshlrev_b32_e32 v162, 16, v163
	v_and_b32_e32 v163, 0xffff0000, v163
	v_pk_add_f32 v[126:127], v[126:127], v[162:163]
	v_lshlrev_b32_e32 v162, 16, v164
	v_and_b32_e32 v163, 0xffff0000, v164
	v_pk_add_f32 v[120:121], v[120:121], v[162:163]
	v_lshlrev_b32_e32 v162, 16, v165
	v_and_b32_e32 v163, 0xffff0000, v165
	v_pk_add_f32 v[124:125], v[124:125], v[166:167]
	v_pk_add_f32 v[122:123], v[122:123], v[162:163]
	s_cbranch_vccnz .LBB0_1234
	global_store_dwordx4 v[152:153], v[124:127], off
	global_store_dwordx4 v[152:153], v[120:123], off offset:16
.LBB0_1234:
	v_mov_b32_e32 v155, v139
	v_lshl_add_u64 v[154:155], s[72:73], 0, v[154:155]
	v_cvt_pk_bf16_f32 v162, v124, v125
	v_cvt_pk_bf16_f32 v163, v126, v127
	v_cvt_pk_bf16_f32 v164, v120, v121
	v_cvt_pk_bf16_f32 v165, v122, v123
	global_store_dwordx4 v[154:155], v[162:165], off
	s_and_b64 vcc, exec, s[40:41]
	s_waitcnt vmcnt(15)
	s_nop 1
	v_mov_b32_e32 v162, v176
	v_mov_b32_e32 v163, v177
	v_mov_b32_e32 v164, v178
	v_mov_b32_e32 v165, v179
	v_lshlrev_b32_e32 v166, 16, v162
	v_and_b32_e32 v167, 0xffff0000, v162
	v_lshlrev_b32_e32 v162, 16, v163
	v_and_b32_e32 v163, 0xffff0000, v163
	v_pk_add_f32 v[118:119], v[118:119], v[162:163]
	v_lshlrev_b32_e32 v162, 16, v164
	v_and_b32_e32 v163, 0xffff0000, v164
	v_pk_add_f32 v[112:113], v[112:113], v[162:163]
	v_lshlrev_b32_e32 v162, 16, v165
	v_and_b32_e32 v163, 0xffff0000, v165
	v_pk_add_f32 v[116:117], v[116:117], v[166:167]
	v_pk_add_f32 v[114:115], v[114:115], v[162:163]
	s_cbranch_vccnz .LBB0_1236
	global_store_dwordx4 v[152:153], v[116:119], off offset:512
	global_store_dwordx4 v[152:153], v[112:115], off offset:528

; __device__ __forceinline__ unsigned cvt_pk_bf16(float lo, float hi) { unsigned r; asm volatile("v_cvt_pk_bf16_f32 %0, %1, %2" : "=v"(r) : "v"(lo), "v"(hi)); return r; }
;     __device__ __forceinline__ void operator()(const f32x4 (&acc)[2][2][4][2], const Unit& u, int wr, int wc, int fr, int fq) const {
;     ...
;                 const unsigned row = row0 + ai * HALF + m * 16;
;                 const unsigned hoff = (row * 1024u + col0) * 2u;
;                 float sq = 0.f;
; #pragma unroll
;                 for (int bj = 0; bj < 2; ++bj) {
;                     const u32x4 xw = *(const u32x4*)(xbp + hoff + bj * (HALF * 2));
;                     f32x4 v0, v1;
;                     v0[0] = __uint_as_float(xw.x << 16) + acc[ai][bj][m][0][0]; v0[1] = __uint_as_float(xw.x & 0xffff0000u) + acc[ai][bj][m][0][1];
;                     v0[2] = __uint_as_float(xw.y << 16) + acc[ai][bj][m][0][2]; v0[3] = __uint_as_float(xw.y & 0xffff0000u) + acc[ai][bj][m][0][3];
;                     v1[0] = __uint_as_float(xw.z << 16) + acc[ai][bj][m][1][0]; v1[1] = __uint_as_float(xw.z & 0xffff0000u) + acc[ai][bj][m][1][1];
;                     v1[2] = __uint_as_float(xw.w << 16) + acc[ai][bj][m][1][2]; v1[3] = __uint_as_float(xw.w & 0xffff0000u) + acc[ai][bj][m][1][3];
;                     if (xout) { *(f32x4*)(xo + 2u * hoff + bj * (HALF * 4)) = v0; *(f32x4*)(xo + 2u * hoff + bj * (HALF * 4) + 16) = v1; }
;                     u32x4 w; w.x = cvt_pk_bf16(v0[0], v0[1]); w.y = cvt_pk_bf16(v0[2], v0[3]); w.z = cvt_pk_bf16(v1[0], v1[1]); w.w = cvt_pk_bf16(v1[2], v1[3]);
;                     *(u32x4*)(xbp + hoff + bj * (HALF * 2)) = w;
;                     sq += (v0[0] * v0[0] + v0[1] * v0[1]) + (v0[2] * v0[2] + v0[3] * v0[3]) + (v1[0] * v1[0] + v1[1] * v1[1]) + (v1[2] * v1[2] + v1[3] * v1[3]);
;                 }
;                 sq += __shfl_xor(sq, 16); sq += __shfl_xor(sq, 32);
;                 if (fq == 0) *(float*)(ssp + row * 64u + ssoff) = sq;
.LBB0_1238:
	s_or_b64 exec, exec, s[24:25]
	v_or_b32_e32 v118, 16, v160
	v_lshl_add_u32 v114, v118, 11, v161
	v_lshlrev_b32_e32 v138, 1, v114
	s_waitcnt lgkmcnt(0)
	v_lshl_add_u64 v[112:113], s[22:23], 0, v[138:139]
	s_and_b64 vcc, exec, s[40:41]
	s_waitcnt vmcnt(16)
	s_nop 1
	v_mov_b32_e32 v120, v180
	v_mov_b32_e32 v121, v181
	v_mov_b32_e32 v122, v182
	v_mov_b32_e32 v123, v183
	v_lshlrev_b32_e32 v124, 16, v120
	v_and_b32_e32 v125, 0xffff0000, v120
	v_lshlrev_b32_e32 v120, 16, v121
	v_and_b32_e32 v121, 0xffff0000, v121
	v_pk_add_f32 v[110:111], v[110:111], v[120:121]
	v_lshlrev_b32_e32 v120, 16, v122
	v_and_b32_e32 v121, 0xffff0000, v122
	v_pk_add_f32 v[104:105], v[104:105], v[120:121]
	v_lshlrev_b32_e32 v120, 16, v123
	v_and_b32_e32 v121, 0xffff0000, v123
	v_pk_add_f32 v[108:109], v[108:109], v[124:125]
	v_pk_add_f32 v[106:107], v[106:107], v[120:121]
	s_cbranch_vccnz .LBB0_1240
	global_store_dwordx4 v[112:113], v[108:111], off
	global_store_dwordx4 v[112:113], v[104:107], off offset:16
.LBB0_1240:
	v_mov_b32_e32 v115, v139
	v_lshl_add_u64 v[114:115], s[72:73], 0, v[114:115]
	v_cvt_pk_bf16_f32 v120, v108, v109
	v_cvt_pk_bf16_f32 v121, v110, v111
	v_cvt_pk_bf16_f32 v122, v104, v105
	v_cvt_pk_bf16_f32 v123, v106, v107
	global_store_dwordx4 v[114:115], v[120:123], off
	s_and_b64 vcc, exec, s[40:41]
	s_waitcnt vmcnt(16)
	s_nop 1
	v_mov_b32_e32 v120, v184
	v_mov_b32_e32 v121, v185
	v_mov_b32_e32 v122, v186
	v_mov_b32_e32 v123, v187
	v_lshlrev_b32_e32 v124, 16, v120
	v_and_b32_e32 v125, 0xffff0000, v120
	v_lshlrev_b32_e32 v120, 16, v121
	v_and_b32_e32 v121, 0xffff0000, v121
	v_pk_add_f32 v[102:103], v[102:103], v[120:121]
	v_lshlrev_b32_e32 v120, 16, v122
	v_and_b32_e32 v121, 0xffff0000, v122
	v_pk_add_f32 v[96:97], v[96:97], v[120:121]
	v_lshlrev_b32_e32 v120, 16, v123
	v_and_b32_e32 v121, 0xffff0000, v123
	v_pk_add_f32 v[100:101], v[100:101], v[124:125]
	v_pk_add_f32 v[98:99], v[98:99], v[120:121]
	s_cbranch_vccnz .LBB0_1242
	global_store_dwordx4 v[112:113], v[100:103], off offset:512
	global_store_dwordx4 v[112:113], v[96:99], off offset:528

; __device__ __forceinline__ unsigned cvt_pk_bf16(float lo, float hi) { unsigned r; asm volatile("v_cvt_pk_bf16_f32 %0, %1, %2" : "=v"(r) : "v"(lo), "v"(hi)); return r; }
;     __device__ __forceinline__ void operator()(const f32x4 (&acc)[2][2][4][2], const Unit& u, int wr, int wc, int fr, int fq) const {
;     ...
;                 const unsigned row = row0 + ai * HALF + m * 16;
;                 const unsigned hoff = (row * 1024u + col0) * 2u;
;                 float sq = 0.f;
; #pragma unroll
;                 for (int bj = 0; bj < 2; ++bj) {
;                     const u32x4 xw = *(const u32x4*)(xbp + hoff + bj * (HALF * 2));
;                     f32x4 v0, v1;
;                     v0[0] = __uint_as_float(xw.x << 16) + acc[ai][bj][m][0][0]; v0[1] = __uint_as_float(xw.x & 0xffff0000u) + acc[ai][bj][m][0][1];
;                     v0[2] = __uint_as_float(xw.y << 16) + acc[ai][bj][m][0][2]; v0[3] = __uint_as_float(xw.y & 0xffff0000u) + acc[ai][bj][m][0][3];
;                     v1[0] = __uint_as_float(xw.z << 16) + acc[ai][bj][m][1][0]; v1[1] = __uint_as_float(xw.z & 0xffff0000u) + acc[ai][bj][m][1][1];
;                     v1[2] = __uint_as_float(xw.w << 16) + acc[ai][bj][m][1][2]; v1[3] = __uint_as_float(xw.w & 0xffff0000u) + acc[ai][bj][m][1][3];
;                     if (xout) { *(f32x4*)(xo + 2u * hoff + bj * (HALF * 4)) = v0; *(f32x4*)(xo + 2u * hoff + bj * (HALF * 4) + 16) = v1; }
;                     u32x4 w; w.x = cvt_pk_bf16(v0[0], v0[1]); w.y = cvt_pk_bf16(v0[2], v0[3]); w.z = cvt_pk_bf16(v1[0], v1[1]); w.w = cvt_pk_bf16(v1[2], v1[3]);
;                     *(u32x4*)(xbp + hoff + bj * (HALF * 2)) = w;
;                     sq += (v0[0] * v0[0] + v0[1] * v0[1]) + (v0[2] * v0[2] + v0[3] * v0[3]) + (v1[0] * v1[0] + v1[1] * v1[1]) + (v1[2] * v1[2] + v1[3] * v1[3]);
;                 }
;                 sq += __shfl_xor(sq, 16); sq += __shfl_xor(sq, 32);
;                 if (fq == 0) *(float*)(ssp + row * 64u + ssoff) = sq;
.LBB0_1244:
	s_or_b64 exec, exec, s[24:25]
	v_or_b32_e32 v100, 32, v160
	v_lshl_add_u32 v98, v100, 11, v161
	v_lshlrev_b32_e32 v138, 1, v98
	s_waitcnt lgkmcnt(0)
	v_lshl_add_u64 v[96:97], s[22:23], 0, v[138:139]
	s_and_b64 vcc, exec, s[40:41]
	s_waitcnt vmcnt(17)
	s_nop 1
	v_mov_b32_e32 v102, v188
	v_mov_b32_e32 v103, v189
	v_mov_b32_e32 v104, v190
	v_mov_b32_e32 v105, v191
	v_lshlrev_b32_e32 v106, 16, v102
	v_and_b32_e32 v107, 0xffff0000, v102
	v_lshlrev_b32_e32 v102, 16, v103
	v_and_b32_e32 v103, 0xffff0000, v103
	v_pk_add_f32 v[94:95], v[94:95], v[102:103]
	v_lshlrev_b32_e32 v102, 16, v104
	v_and_b32_e32 v103, 0xffff0000, v104
	v_pk_add_f32 v[88:89], v[88:89], v[102:103]
	v_lshlrev_b32_e32 v102, 16, v105
	v_and_b32_e32 v103, 0xffff0000, v105
	v_pk_add_f32 v[92:93], v[92:93], v[106:107]
	v_pk_add_f32 v[90:91], v[90:91], v[102:103]
	s_cbranch_vccnz .LBB0_1246
	global_store_dwordx4 v[96:97], v[92:95], off
	global_store_dwordx4 v[96:97], v[88:91], off offset:16
.LBB0_1246:
	v_mov_b32_e32 v99, v139
	v_lshl_add_u64 v[98:99], s[72:73], 0, v[98:99]
	v_cvt_pk_bf16_f32 v102, v92, v93
	v_cvt_pk_bf16_f32 v103, v94, v95
	v_cvt_pk_bf16_f32 v104, v88, v89
	v_cvt_pk_bf16_f32 v105, v90, v91
	global_store_dwordx4 v[98:99], v[102:105], off
	s_and_b64 vcc, exec, s[40:41]
	s_waitcnt vmcnt(17)
	s_nop 1
	v_mov_b32_e32 v102, v192
	v_mov_b32_e32 v103, v193
	v_mov_b32_e32 v104, v194
	v_mov_b32_e32 v105, v195
	v_lshlrev_b32_e32 v106, 16, v102
	v_and_b32_e32 v107, 0xffff0000, v102
	v_lshlrev_b32_e32 v102, 16, v103
	v_and_b32_e32 v103, 0xffff0000, v103
	v_pk_add_f32 v[86:87], v[86:87], v[102:103]
	v_lshlrev_b32_e32 v102, 16, v104
	v_and_b32_e32 v103, 0xffff0000, v104
	v_pk_add_f32 v[80:81], v[80:81], v[102:103]
	v_lshlrev_b32_e32 v102, 16, v105
	v_and_b32_e32 v103, 0xffff0000, v105
	v_pk_add_f32 v[84:85], v[84:85], v[106:107]
	v_pk_add_f32 v[82:83], v[82:83], v[102:103]
	s_cbranch_vccnz .LBB0_1248
	global_store_dwordx4 v[96:97], v[84:87], off offset:512
	global_store_dwordx4 v[96:97], v[80:83], off offset:528

; __device__ __forceinline__ unsigned cvt_pk_bf16(float lo, float hi) { unsigned r; asm volatile("v_cvt_pk_bf16_f32 %0, %1, %2" : "=v"(r) : "v"(lo), "v"(hi)); return r; }
;     __device__ __forceinline__ void operator()(const f32x4 (&acc)[2][2][4][2], const Unit& u, int wr, int wc, int fr, int fq) const {
;     ...
;                 const unsigned row = row0 + ai * HALF + m * 16;
;                 const unsigned hoff = (row * 1024u + col0) * 2u;
;                 float sq = 0.f;
; #pragma unroll
;                 for (int bj = 0; bj < 2; ++bj) {
;                     const u32x4 xw = *(const u32x4*)(xbp + hoff + bj * (HALF * 2));
;                     f32x4 v0, v1;
;                     v0[0] = __uint_as_float(xw.x << 16) + acc[ai][bj][m][0][0]; v0[1] = __uint_as_float(xw.x & 0xffff0000u) + acc[ai][bj][m][0][1];
;                     v0[2] = __uint_as_float(xw.y << 16) + acc[ai][bj][m][0][2]; v0[3] = __uint_as_float(xw.y & 0xffff0000u) + acc[ai][bj][m][0][3];
;                     v1[0] = __uint_as_float(xw.z << 16) + acc[ai][bj][m][1][0]; v1[1] = __uint_as_float(xw.z & 0xffff0000u) + acc[ai][bj][m][1][1];
;                     v1[2] = __uint_as_float(xw.w << 16) + acc[ai][bj][m][1][2]; v1[3] = __uint_as_float(xw.w & 0xffff0000u) + acc[ai][bj][m][1][3];
;                     if (xout) { *(f32x4*)(xo + 2u * hoff + bj * (HALF * 4)) = v0; *(f32x4*)(xo + 2u * hoff + bj * (HALF * 4) + 16) = v1; }
;                     u32x4 w; w.x = cvt_pk_bf16(v0[0], v0[1]); w.y = cvt_pk_bf16(v0[2], v0[3]); w.z = cvt_pk_bf16(v1[0], v1[1]); w.w = cvt_pk_bf16(v1[2], v1[3]);
;                     *(u32x4*)(xbp + hoff + bj * (HALF * 2)) = w;
;                     sq += (v0[0] * v0[0] + v0[1] * v0[1]) + (v0[2] * v0[2] + v0[3] * v0[3]) + (v1[0] * v1[0] + v1[1] * v1[1]) + (v1[2] * v1[2] + v1[3] * v1[3]);
;                 }
;                 sq += __shfl_xor(sq, 16); sq += __shfl_xor(sq, 32);
;                 if (fq == 0) *(float*)(ssp + row * 64u + ssoff) = sq;
.LBB0_1250:
	s_or_b64 exec, exec, s[24:25]
	v_or_b32_e32 v84, 48, v160
	v_lshl_add_u32 v82, v84, 11, v161
	v_lshlrev_b32_e32 v138, 1, v82
	s_waitcnt lgkmcnt(0)
	v_lshl_add_u64 v[80:81], s[22:23], 0, v[138:139]
	s_and_b64 vcc, exec, s[40:41]
	s_waitcnt vmcnt(18)
	s_nop 1
	v_mov_b32_e32 v86, v196
	v_mov_b32_e32 v87, v197
	v_mov_b32_e32 v88, v198
	v_mov_b32_e32 v89, v199
	v_lshlrev_b32_e32 v90, 16, v86
	v_and_b32_e32 v91, 0xffff0000, v86
	v_lshlrev_b32_e32 v86, 16, v87
	v_and_b32_e32 v87, 0xffff0000, v87
	v_pk_add_f32 v[78:79], v[78:79], v[86:87]
	v_lshlrev_b32_e32 v86, 16, v88
	v_and_b32_e32 v87, 0xffff0000, v88
	v_pk_add_f32 v[72:73], v[72:73], v[86:87]
	v_lshlrev_b32_e32 v86, 16, v89
	v_and_b32_e32 v87, 0xffff0000, v89
	v_pk_add_f32 v[76:77], v[76:77], v[90:91]
	v_pk_add_f32 v[74:75], v[74:75], v[86:87]
	s_cbranch_vccnz .LBB0_1252
	global_store_dwordx4 v[80:81], v[76:79], off
	global_store_dwordx4 v[80:81], v[72:75], off offset:16
.LBB0_1252:
	v_mov_b32_e32 v83, v139
	v_lshl_add_u64 v[82:83], s[72:73], 0, v[82:83]
	v_cvt_pk_bf16_f32 v86, v76, v77
	v_cvt_pk_bf16_f32 v87, v78, v79
	v_cvt_pk_bf16_f32 v88, v72, v73
	v_cvt_pk_bf16_f32 v89, v74, v75
	global_store_dwordx4 v[82:83], v[86:89], off
	s_and_b64 vcc, exec, s[40:41]
	s_waitcnt vmcnt(18)
	s_nop 1
	v_mov_b32_e32 v86, v200
	v_mov_b32_e32 v87, v201
	v_mov_b32_e32 v88, v202
	v_mov_b32_e32 v89, v203
	v_lshlrev_b32_e32 v90, 16, v86
	v_and_b32_e32 v91, 0xffff0000, v86
	v_lshlrev_b32_e32 v86, 16, v87
	v_and_b32_e32 v87, 0xffff0000, v87
	v_pk_add_f32 v[70:71], v[70:71], v[86:87]
	v_lshlrev_b32_e32 v86, 16, v88
	v_and_b32_e32 v87, 0xffff0000, v88
	v_pk_add_f32 v[64:65], v[64:65], v[86:87]
	v_lshlrev_b32_e32 v86, 16, v89
	v_and_b32_e32 v87, 0xffff0000, v89
	v_pk_add_f32 v[68:69], v[68:69], v[90:91]
	v_pk_add_f32 v[66:67], v[66:67], v[86:87]
	s_cbranch_vccnz .LBB0_1254
	global_store_dwordx4 v[80:81], v[68:71], off offset:512
	global_store_dwordx4 v[80:81], v[64:67], off offset:528

; __device__ __forceinline__ unsigned cvt_pk_bf16(float lo, float hi) { unsigned r; asm volatile("v_cvt_pk_bf16_f32 %0, %1, %2" : "=v"(r) : "v"(lo), "v"(hi)); return r; }
;     __device__ __forceinline__ void operator()(const f32x4 (&acc)[2][2][4][2], const Unit& u, int wr, int wc, int fr, int fq) const {
;     ...
;                 const unsigned row = row0 + ai * HALF + m * 16;
;                 const unsigned hoff = (row * 1024u + col0) * 2u;
;                 float sq = 0.f;
; #pragma unroll
;                 for (int bj = 0; bj < 2; ++bj) {
;                     const u32x4 xw = *(const u32x4*)(xbp + hoff + bj * (HALF * 2));
;                     f32x4 v0, v1;
;                     v0[0] = __uint_as_float(xw.x << 16) + acc[ai][bj][m][0][0]; v0[1] = __uint_as_float(xw.x & 0xffff0000u) + acc[ai][bj][m][0][1];
;                     v0[2] = __uint_as_float(xw.y << 16) + acc[ai][bj][m][0][2]; v0[3] = __uint_as_float(xw.y & 0xffff0000u) + acc[ai][bj][m][0][3];
;                     v1[0] = __uint_as_float(xw.z << 16) + acc[ai][bj][m][1][0]; v1[1] = __uint_as_float(xw.z & 0xffff0000u) + acc[ai][bj][m][1][1];
;                     v1[2] = __uint_as_float(xw.w << 16) + acc[ai][bj][m][1][2]; v1[3] = __uint_as_float(xw.w & 0xffff0000u) + acc[ai][bj][m][1][3];
;                     if (xout) { *(f32x4*)(xo + 2u * hoff + bj * (HALF * 4)) = v0; *(f32x4*)(xo + 2u * hoff + bj * (HALF * 4) + 16) = v1; }
;                     u32x4 w; w.x = cvt_pk_bf16(v0[0], v0[1]); w.y = cvt_pk_bf16(v0[2], v0[3]); w.z = cvt_pk_bf16(v1[0], v1[1]); w.w = cvt_pk_bf16(v1[2], v1[3]);
;                     *(u32x4*)(xbp + hoff + bj * (HALF * 2)) = w;
;                     sq += (v0[0] * v0[0] + v0[1] * v0[1]) + (v0[2] * v0[2] + v0[3] * v0[3]) + (v1[0] * v1[0] + v1[1] * v1[1]) + (v1[2] * v1[2] + v1[3] * v1[3]);
;                 }
;                 sq += __shfl_xor(sq, 16); sq += __shfl_xor(sq, 32);
;                 if (fq == 0) *(float*)(ssp + row * 64u + ssoff) = sq;
.LBB0_1256:
	s_or_b64 exec, exec, s[24:25]
	v_add_u32_e32 v68, 0x80, v160
	v_lshl_add_u32 v66, v68, 11, v161
	v_lshlrev_b32_e32 v138, 1, v66
	s_waitcnt lgkmcnt(0)
	v_lshl_add_u64 v[64:65], s[22:23], 0, v[138:139]
	s_and_b64 vcc, exec, s[40:41]
	s_waitcnt vmcnt(19)
	s_nop 1
	v_mov_b32_e32 v70, v208
	v_mov_b32_e32 v71, v209
	v_mov_b32_e32 v72, v210
	v_mov_b32_e32 v73, v211
	v_lshlrev_b32_e32 v74, 16, v70
	v_and_b32_e32 v75, 0xffff0000, v70
	v_lshlrev_b32_e32 v70, 16, v71
	v_and_b32_e32 v71, 0xffff0000, v71
	v_pk_add_f32 v[62:63], v[62:63], v[70:71]
	v_lshlrev_b32_e32 v70, 16, v72
	v_and_b32_e32 v71, 0xffff0000, v72
	v_pk_add_f32 v[56:57], v[56:57], v[70:71]
	v_lshlrev_b32_e32 v70, 16, v73
	v_and_b32_e32 v71, 0xffff0000, v73
	v_pk_add_f32 v[60:61], v[60:61], v[74:75]
	v_pk_add_f32 v[58:59], v[58:59], v[70:71]
	s_cbranch_vccnz .LBB0_1258
	global_store_dwordx4 v[64:65], v[60:63], off
	global_store_dwordx4 v[64:65], v[56:59], off offset:16
.LBB0_1258:
	v_mov_b32_e32 v67, v139
	v_lshl_add_u64 v[66:67], s[72:73], 0, v[66:67]
	v_cvt_pk_bf16_f32 v70, v60, v61
	v_cvt_pk_bf16_f32 v71, v62, v63
	v_cvt_pk_bf16_f32 v72, v56, v57
	v_cvt_pk_bf16_f32 v73, v58, v59
	global_store_dwordx4 v[66:67], v[70:73], off
	s_and_b64 vcc, exec, s[40:41]
	s_waitcnt vmcnt(19)
	s_nop 1
	v_mov_b32_e32 v70, v212
	v_mov_b32_e32 v71, v213
	v_mov_b32_e32 v72, v214
	v_mov_b32_e32 v73, v215
	v_lshlrev_b32_e32 v74, 16, v70
	v_and_b32_e32 v75, 0xffff0000, v70
	v_lshlrev_b32_e32 v70, 16, v71
	v_and_b32_e32 v71, 0xffff0000, v71
	v_pk_add_f32 v[54:55], v[54:55], v[70:71]
	v_lshlrev_b32_e32 v70, 16, v72
	v_and_b32_e32 v71, 0xffff0000, v72
	v_pk_add_f32 v[48:49], v[48:49], v[70:71]
	v_lshlrev_b32_e32 v70, 16, v73
	v_and_b32_e32 v71, 0xffff0000, v73
	v_pk_add_f32 v[52:53], v[52:53], v[74:75]
	v_pk_add_f32 v[50:51], v[50:51], v[70:71]
	s_cbranch_vccnz .LBB0_1260
	global_store_dwordx4 v[64:65], v[52:55], off offset:512
	global_store_dwordx4 v[64:65], v[48:51], off offset:528

; __device__ __forceinline__ unsigned cvt_pk_bf16(float lo, float hi) { unsigned r; asm volatile("v_cvt_pk_bf16_f32 %0, %1, %2" : "=v"(r) : "v"(lo), "v"(hi)); return r; }
;     __device__ __forceinline__ void operator()(const f32x4 (&acc)[2][2][4][2], const Unit& u, int wr, int wc, int fr, int fq) const {
;     ...
;                 const unsigned row = row0 + ai * HALF + m * 16;
;                 const unsigned hoff = (row * 1024u + col0) * 2u;
;                 float sq = 0.f;
; #pragma unroll
;                 for (int bj = 0; bj < 2; ++bj) {
;                     const u32x4 xw = *(const u32x4*)(xbp + hoff + bj * (HALF * 2));
;                     f32x4 v0, v1;
;                     v0[0] = __uint_as_float(xw.x << 16) + acc[ai][bj][m][0][0]; v0[1] = __uint_as_float(xw.x & 0xffff0000u) + acc[ai][bj][m][0][1];
;                     v0[2] = __uint_as_float(xw.y << 16) + acc[ai][bj][m][0][2]; v0[3] = __uint_as_float(xw.y & 0xffff0000u) + acc[ai][bj][m][0][3];
;                     v1[0] = __uint_as_float(xw.z << 16) + acc[ai][bj][m][1][0]; v1[1] = __uint_as_float(xw.z & 0xffff0000u) + acc[ai][bj][m][1][1];
;                     v1[2] = __uint_as_float(xw.w << 16) + acc[ai][bj][m][1][2]; v1[3] = __uint_as_float(xw.w & 0xffff0000u) + acc[ai][bj][m][1][3];
;                     if (xout) { *(f32x4*)(xo + 2u * hoff + bj * (HALF * 4)) = v0; *(f32x4*)(xo + 2u * hoff + bj * (HALF * 4) + 16) = v1; }
;                     u32x4 w; w.x = cvt_pk_bf16(v0[0], v0[1]); w.y = cvt_pk_bf16(v0[2], v0[3]); w.z = cvt_pk_bf16(v1[0], v1[1]); w.w = cvt_pk_bf16(v1[2], v1[3]);
;                     *(u32x4*)(xbp + hoff + bj * (HALF * 2)) = w;
;                     sq += (v0[0] * v0[0] + v0[1] * v0[1]) + (v0[2] * v0[2] + v0[3] * v0[3]) + (v1[0] * v1[0] + v1[1] * v1[1]) + (v1[2] * v1[2] + v1[3] * v1[3]);
;                 }
;                 sq += __shfl_xor(sq, 16); sq += __shfl_xor(sq, 32);
;                 if (fq == 0) *(float*)(ssp + row * 64u + ssoff) = sq;
.LBB0_1262:
	s_or_b64 exec, exec, s[24:25]
	v_add_u32_e32 v52, 0x90, v160
	v_lshl_add_u32 v50, v52, 11, v161
	v_lshlrev_b32_e32 v138, 1, v50
	s_waitcnt lgkmcnt(0)
	v_lshl_add_u64 v[48:49], s[22:23], 0, v[138:139]
	s_and_b64 vcc, exec, s[40:41]
	s_waitcnt vmcnt(20)
	s_nop 1
	v_mov_b32_e32 v54, v216
	v_mov_b32_e32 v55, v217
	v_mov_b32_e32 v56, v218
	v_mov_b32_e32 v57, v219
	v_lshlrev_b32_e32 v58, 16, v54
	v_and_b32_e32 v59, 0xffff0000, v54
	v_lshlrev_b32_e32 v54, 16, v55
	v_and_b32_e32 v55, 0xffff0000, v55
	v_pk_add_f32 v[46:47], v[46:47], v[54:55]
	v_lshlrev_b32_e32 v54, 16, v56
	v_and_b32_e32 v55, 0xffff0000, v56
	v_pk_add_f32 v[40:41], v[40:41], v[54:55]
	v_lshlrev_b32_e32 v54, 16, v57
	v_and_b32_e32 v55, 0xffff0000, v57
	v_pk_add_f32 v[44:45], v[44:45], v[58:59]
	v_pk_add_f32 v[42:43], v[42:43], v[54:55]
	s_cbranch_vccnz .LBB0_1264
	global_store_dwordx4 v[48:49], v[44:47], off
	global_store_dwordx4 v[48:49], v[40:43], off offset:16
.LBB0_1264:
	v_mov_b32_e32 v51, v139
	v_lshl_add_u64 v[50:51], s[72:73], 0, v[50:51]
	v_cvt_pk_bf16_f32 v54, v44, v45
	v_cvt_pk_bf16_f32 v55, v46, v47
	v_cvt_pk_bf16_f32 v56, v40, v41
	v_cvt_pk_bf16_f32 v57, v42, v43
	global_store_dwordx4 v[50:51], v[54:57], off
	s_and_b64 vcc, exec, s[40:41]
	s_waitcnt vmcnt(20)
	s_nop 1
	v_mov_b32_e32 v54, v220
	v_mov_b32_e32 v55, v221
	v_mov_b32_e32 v56, v222
	v_mov_b32_e32 v57, v223
	v_lshlrev_b32_e32 v58, 16, v54
	v_and_b32_e32 v59, 0xffff0000, v54
	v_lshlrev_b32_e32 v54, 16, v55
	v_and_b32_e32 v55, 0xffff0000, v55
	v_pk_add_f32 v[38:39], v[38:39], v[54:55]
	v_lshlrev_b32_e32 v54, 16, v56
	v_and_b32_e32 v55, 0xffff0000, v56
	v_pk_add_f32 v[32:33], v[32:33], v[54:55]
	v_lshlrev_b32_e32 v54, 16, v57
	v_and_b32_e32 v55, 0xffff0000, v57
	v_pk_add_f32 v[36:37], v[36:37], v[58:59]
	v_pk_add_f32 v[34:35], v[34:35], v[54:55]
	s_cbranch_vccnz .LBB0_1266
	global_store_dwordx4 v[48:49], v[36:39], off offset:512
	global_store_dwordx4 v[48:49], v[32:35], off offset:528

; __device__ __forceinline__ unsigned cvt_pk_bf16(float lo, float hi) { unsigned r; asm volatile("v_cvt_pk_bf16_f32 %0, %1, %2" : "=v"(r) : "v"(lo), "v"(hi)); return r; }
;     __device__ __forceinline__ void operator()(const f32x4 (&acc)[2][2][4][2], const Unit& u, int wr, int wc, int fr, int fq) const {
;     ...
;                 const unsigned row = row0 + ai * HALF + m * 16;
;                 const unsigned hoff = (row * 1024u + col0) * 2u;
;                 float sq = 0.f;
; #pragma unroll
;                 for (int bj = 0; bj < 2; ++bj) {
;                     const u32x4 xw = *(const u32x4*)(xbp + hoff + bj * (HALF * 2));
;                     f32x4 v0, v1;
;                     v0[0] = __uint_as_float(xw.x << 16) + acc[ai][bj][m][0][0]; v0[1] = __uint_as_float(xw.x & 0xffff0000u) + acc[ai][bj][m][0][1];
;                     v0[2] = __uint_as_float(xw.y << 16) + acc[ai][bj][m][0][2]; v0[3] = __uint_as_float(xw.y & 0xffff0000u) + acc[ai][bj][m][0][3];
;                     v1[0] = __uint_as_float(xw.z << 16) + acc[ai][bj][m][1][0]; v1[1] = __uint_as_float(xw.z & 0xffff0000u) + acc[ai][bj][m][1][1];
;                     v1[2] = __uint_as_float(xw.w << 16) + acc[ai][bj][m][1][2]; v1[3] = __uint_as_float(xw.w & 0xffff0000u) + acc[ai][bj][m][1][3];
;                     if (xout) { *(f32x4*)(xo + 2u * hoff + bj * (HALF * 4)) = v0; *(f32x4*)(xo + 2u * hoff + bj * (HALF * 4) + 16) = v1; }
;                     u32x4 w; w.x = cvt_pk_bf16(v0[0], v0[1]); w.y = cvt_pk_bf16(v0[2], v0[3]); w.z = cvt_pk_bf16(v1[0], v1[1]); w.w = cvt_pk_bf16(v1[2], v1[3]);
;                     *(u32x4*)(xbp + hoff + bj * (HALF * 2)) = w;
;                     sq += (v0[0] * v0[0] + v0[1] * v0[1]) + (v0[2] * v0[2] + v0[3] * v0[3]) + (v1[0] * v1[0] + v1[1] * v1[1]) + (v1[2] * v1[2] + v1[3] * v1[3]);
;                 }
;                 sq += __shfl_xor(sq, 16); sq += __shfl_xor(sq, 32);
;                 if (fq == 0) *(float*)(ssp + row * 64u + ssoff) = sq;
.LBB0_1268:
	s_or_b64 exec, exec, s[24:25]
	v_add_u32_e32 v36, 0xa0, v160
	v_lshl_add_u32 v34, v36, 11, v161
	v_lshlrev_b32_e32 v138, 1, v34
	s_waitcnt lgkmcnt(0)
	v_lshl_add_u64 v[32:33], s[22:23], 0, v[138:139]
	s_and_b64 vcc, exec, s[40:41]
	s_waitcnt vmcnt(21)
	s_nop 1
	v_mov_b32_e32 v38, v224
	v_mov_b32_e32 v39, v225
	v_mov_b32_e32 v40, v226
	v_mov_b32_e32 v41, v227
	v_lshlrev_b32_e32 v42, 16, v38
	v_and_b32_e32 v43, 0xffff0000, v38
	v_lshlrev_b32_e32 v38, 16, v39
	v_and_b32_e32 v39, 0xffff0000, v39
	v_pk_add_f32 v[30:31], v[30:31], v[38:39]
	v_lshlrev_b32_e32 v38, 16, v40
	v_and_b32_e32 v39, 0xffff0000, v40
	v_pk_add_f32 v[24:25], v[24:25], v[38:39]
	v_lshlrev_b32_e32 v38, 16, v41
	v_and_b32_e32 v39, 0xffff0000, v41
	v_pk_add_f32 v[28:29], v[28:29], v[42:43]
	v_pk_add_f32 v[26:27], v[26:27], v[38:39]
	s_cbranch_vccnz .LBB0_1270
	global_store_dwordx4 v[32:33], v[28:31], off
	global_store_dwordx4 v[32:33], v[24:27], off offset:16
.LBB0_1270:
	v_mov_b32_e32 v35, v139
	v_lshl_add_u64 v[34:35], s[72:73], 0, v[34:35]
	v_cvt_pk_bf16_f32 v38, v28, v29
	v_cvt_pk_bf16_f32 v39, v30, v31
	v_cvt_pk_bf16_f32 v40, v24, v25
	v_cvt_pk_bf16_f32 v41, v26, v27
	global_store_dwordx4 v[34:35], v[38:41], off
	s_and_b64 vcc, exec, s[40:41]
	s_waitcnt vmcnt(21)
	s_nop 1
	v_mov_b32_e32 v38, v228
	v_mov_b32_e32 v39, v229
	v_mov_b32_e32 v40, v230
	v_mov_b32_e32 v41, v231
	v_lshlrev_b32_e32 v42, 16, v38
	v_and_b32_e32 v43, 0xffff0000, v38
	v_lshlrev_b32_e32 v38, 16, v39
	v_and_b32_e32 v39, 0xffff0000, v39
	v_pk_add_f32 v[22:23], v[22:23], v[38:39]
	v_lshlrev_b32_e32 v38, 16, v40
	v_and_b32_e32 v39, 0xffff0000, v40
	v_pk_add_f32 v[16:17], v[16:17], v[38:39]
	v_lshlrev_b32_e32 v38, 16, v41
	v_and_b32_e32 v39, 0xffff0000, v41
	v_pk_add_f32 v[20:21], v[20:21], v[42:43]
	v_pk_add_f32 v[18:19], v[18:19], v[38:39]
	s_cbranch_vccnz .LBB0_1272
	global_store_dwordx4 v[32:33], v[20:23], off offset:512
	global_store_dwordx4 v[32:33], v[16:19], off offset:528

; __device__ __forceinline__ unsigned cvt_pk_bf16(float lo, float hi) { unsigned r; asm volatile("v_cvt_pk_bf16_f32 %0, %1, %2" : "=v"(r) : "v"(lo), "v"(hi)); return r; }
;     __device__ __forceinline__ void operator()(const f32x4 (&acc)[2][2][4][2], const Unit& u, int wr, int wc, int fr, int fq) const {
;     ...
;                 const unsigned row = row0 + ai * HALF + m * 16;
;                 const unsigned hoff = (row * 1024u + col0) * 2u;
;                 float sq = 0.f;
; #pragma unroll
;                 for (int bj = 0; bj < 2; ++bj) {
;                     const u32x4 xw = *(const u32x4*)(xbp + hoff + bj * (HALF * 2));
;                     f32x4 v0, v1;
;                     v0[0] = __uint_as_float(xw.x << 16) + acc[ai][bj][m][0][0]; v0[1] = __uint_as_float(xw.x & 0xffff0000u) + acc[ai][bj][m][0][1];
;                     v0[2] = __uint_as_float(xw.y << 16) + acc[ai][bj][m][0][2]; v0[3] = __uint_as_float(xw.y & 0xffff0000u) + acc[ai][bj][m][0][3];
;                     v1[0] = __uint_as_float(xw.z << 16) + acc[ai][bj][m][1][0]; v1[1] = __uint_as_float(xw.z & 0xffff0000u) + acc[ai][bj][m][1][1];
;                     v1[2] = __uint_as_float(xw.w << 16) + acc[ai][bj][m][1][2]; v1[3] = __uint_as_float(xw.w & 0xffff0000u) + acc[ai][bj][m][1][3];
;                     if (xout) { *(f32x4*)(xo + 2u * hoff + bj * (HALF * 4)) = v0; *(f32x4*)(xo + 2u * hoff + bj * (HALF * 4) + 16) = v1; }
;                     u32x4 w; w.x = cvt_pk_bf16(v0[0], v0[1]); w.y = cvt_pk_bf16(v0[2], v0[3]); w.z = cvt_pk_bf16(v1[0], v1[1]); w.w = cvt_pk_bf16(v1[2], v1[3]);
;                     *(u32x4*)(xbp + hoff + bj * (HALF * 2)) = w;
;                     sq += (v0[0] * v0[0] + v0[1] * v0[1]) + (v0[2] * v0[2] + v0[3] * v0[3]) + (v1[0] * v1[0] + v1[1] * v1[1]) + (v1[2] * v1[2] + v1[3] * v1[3]);
;                 }
;                 sq += __shfl_xor(sq, 16); sq += __shfl_xor(sq, 32);
;                 if (fq == 0) *(float*)(ssp + row * 64u + ssoff) = sq;
.LBB0_1274:
	s_or_b64 exec, exec, s[24:25]
	v_add_u32_e32 v20, 0xb0, v160
	v_lshl_add_u32 v18, v20, 11, v161
	v_lshlrev_b32_e32 v138, 1, v18
	s_waitcnt lgkmcnt(0)
	v_lshl_add_u64 v[16:17], s[22:23], 0, v[138:139]
	s_and_b64 vcc, exec, s[40:41]
	s_waitcnt vmcnt(22)
	s_nop 1
	v_mov_b32_e32 v22, v232
	v_mov_b32_e32 v23, v233
	v_mov_b32_e32 v24, v234
	v_mov_b32_e32 v25, v235
	v_lshlrev_b32_e32 v26, 16, v22
	v_and_b32_e32 v27, 0xffff0000, v22
	v_lshlrev_b32_e32 v22, 16, v23
	v_and_b32_e32 v23, 0xffff0000, v23
	v_pk_add_f32 v[14:15], v[14:15], v[22:23]
	v_lshlrev_b32_e32 v22, 16, v24
	v_and_b32_e32 v23, 0xffff0000, v24
	v_pk_add_f32 v[8:9], v[8:9], v[22:23]
	v_lshlrev_b32_e32 v22, 16, v25
	v_and_b32_e32 v23, 0xffff0000, v25
	v_pk_add_f32 v[12:13], v[12:13], v[26:27]
	v_pk_add_f32 v[10:11], v[10:11], v[22:23]
	s_cbranch_vccnz .LBB0_1276
	global_store_dwordx4 v[16:17], v[12:15], off
	global_store_dwordx4 v[16:17], v[8:11], off offset:16
.LBB0_1276:
	v_mov_b32_e32 v19, v139
	v_lshl_add_u64 v[18:19], s[72:73], 0, v[18:19]
	v_cvt_pk_bf16_f32 v22, v12, v13
	v_cvt_pk_bf16_f32 v23, v14, v15
	v_cvt_pk_bf16_f32 v24, v8, v9
	v_cvt_pk_bf16_f32 v25, v10, v11
	global_store_dwordx4 v[18:19], v[22:25], off
	s_and_b64 vcc, exec, s[40:41]
	s_waitcnt vmcnt(22)
	s_nop 1
	v_mov_b32_e32 v22, v236
	v_mov_b32_e32 v23, v237
	v_mov_b32_e32 v24, v238
	v_mov_b32_e32 v25, v239
	v_lshlrev_b32_e32 v26, 16, v22
	v_and_b32_e32 v27, 0xffff0000, v22
	v_lshlrev_b32_e32 v22, 16, v23
	v_and_b32_e32 v23, 0xffff0000, v23
	v_pk_add_f32 v[6:7], v[6:7], v[22:23]
	v_lshlrev_b32_e32 v22, 16, v24
	v_and_b32_e32 v23, 0xffff0000, v24
	v_pk_add_f32 v[0:1], v[0:1], v[22:23]
	v_lshlrev_b32_e32 v22, 16, v25
	v_and_b32_e32 v23, 0xffff0000, v25
	v_pk_add_f32 v[4:5], v[4:5], v[26:27]
	v_pk_add_f32 v[2:3], v[2:3], v[22:23]
	s_cbranch_vccnz .LBB0_1278
	global_store_dwordx4 v[16:17], v[4:7], off offset:512
	global_store_dwordx4 v[16:17], v[0:3], off offset:528
